# GEMM K-loops: removed the redundant back-to-back s_setprio 0/1 pair in the middle of each 32-MFMA compute section (8 loops x 4 phases); timing-only
# speedup vs baseline: 1.0475x; 1.0040x over previous
.LBB0_163:
	ds_read_b128 v[148:151], v177
	ds_read_b128 v[152:155], v177 offset:1024
	ds_read_b128 v[156:159], v177 offset:2048
	ds_read_b128 v[182:185], v177 offset:3072
	ds_read_b128 v[186:189], v178
	ds_read_b128 v[190:193], v178 offset:1024
	ds_read_b128 v[194:197], v178 offset:2048
	ds_read_b128 v[198:201], v178 offset:3072
	s_add_u32 s36, s34, 0xfff80080
	s_addc_u32 s37, s35, -1
	s_cmp_eq_u32 s64, 28
	s_cselect_b32 s39, s2, s37
	s_cselect_b32 s38, s3, s36
	s_cselect_b32 s37, s7, s63
	s_cselect_b32 s36, s23, s25
	v_lshl_add_u64 v[160:161], s[34:35], 0, v[142:143]
	s_add_i32 m0, s31, 0xc000
	ds_read_b128 v[202:205], v180
	ds_read_b128 v[210:213], v180 offset:1024
	ds_read_b128 v[214:217], v180 offset:2048
	ds_read_b128 v[218:221], v180 offset:3072
	ds_read_b128 v[222:225], v180 offset:4096
	ds_read_b128 v[226:229], v180 offset:5120
	ds_read_b128 v[230:233], v180 offset:6144
	ds_read_b128 v[234:237], v180 offset:7168
	global_load_lds_dwordx4 v[160:161], off
	v_lshl_add_u64 v[160:161], s[34:35], 0, v[144:145]
	s_add_i32 m0, s31, 0xe000
	s_nop 0
	global_load_lds_dwordx4 v[160:161], off
	s_waitcnt vmcnt(8)
	s_waitcnt lgkmcnt(0)
	s_barrier
	s_setprio 1
	s_waitcnt lgkmcnt(0)
	v_mfma_f32_16x16x32_bf16 v[124:127], v[148:151], v[202:205], v[124:127]
	v_mfma_f32_16x16x32_bf16 v[120:123], v[156:159], v[202:205], v[120:123]
	v_mfma_f32_16x16x32_bf16 v[108:111], v[148:151], v[214:217], v[108:111]
	v_mfma_f32_16x16x32_bf16 v[104:107], v[156:159], v[214:217], v[104:107]
	v_mfma_f32_16x16x32_bf16 v[92:95], v[148:151], v[222:225], v[92:95]
	v_mfma_f32_16x16x32_bf16 v[88:91], v[156:159], v[222:225], v[88:91]
	v_mfma_f32_16x16x32_bf16 v[76:79], v[148:151], v[230:233], v[76:79]
	v_mfma_f32_16x16x32_bf16 v[72:75], v[156:159], v[230:233], v[72:75]
	v_mfma_f32_16x16x32_bf16 v[124:127], v[152:155], v[210:213], v[124:127]
	v_mfma_f32_16x16x32_bf16 v[120:123], v[182:185], v[210:213], v[120:123]
	v_mfma_f32_16x16x32_bf16 v[108:111], v[152:155], v[218:221], v[108:111]
	v_mfma_f32_16x16x32_bf16 v[104:107], v[182:185], v[218:221], v[104:107]
	v_mfma_f32_16x16x32_bf16 v[92:95], v[152:155], v[226:229], v[92:95]
	v_mfma_f32_16x16x32_bf16 v[88:91], v[182:185], v[226:229], v[88:91]
	v_mfma_f32_16x16x32_bf16 v[76:79], v[152:155], v[234:237], v[76:79]
	v_mfma_f32_16x16x32_bf16 v[72:75], v[182:185], v[234:237], v[72:75]
	v_mfma_f32_16x16x32_bf16 v[116:119], v[186:189], v[202:205], v[116:119]
	v_mfma_f32_16x16x32_bf16 v[112:115], v[194:197], v[202:205], v[112:115]
	v_mfma_f32_16x16x32_bf16 v[100:103], v[186:189], v[214:217], v[100:103]
	v_mfma_f32_16x16x32_bf16 v[96:99], v[194:197], v[214:217], v[96:99]
	v_mfma_f32_16x16x32_bf16 v[84:87], v[186:189], v[222:225], v[84:87]
	v_mfma_f32_16x16x32_bf16 v[80:83], v[194:197], v[222:225], v[80:83]
	v_mfma_f32_16x16x32_bf16 v[68:71], v[186:189], v[230:233], v[68:71]
	v_mfma_f32_16x16x32_bf16 v[64:67], v[194:197], v[230:233], v[64:67]
	v_mfma_f32_16x16x32_bf16 v[116:119], v[190:193], v[210:213], v[116:119]
	v_mfma_f32_16x16x32_bf16 v[112:115], v[198:201], v[210:213], v[112:115]
	v_mfma_f32_16x16x32_bf16 v[100:103], v[190:193], v[218:221], v[100:103]
	v_mfma_f32_16x16x32_bf16 v[96:99], v[198:201], v[218:221], v[96:99]
	v_mfma_f32_16x16x32_bf16 v[84:87], v[190:193], v[226:229], v[84:87]
	v_mfma_f32_16x16x32_bf16 v[80:83], v[198:201], v[226:229], v[80:83]
	v_mfma_f32_16x16x32_bf16 v[68:71], v[190:193], v[234:237], v[68:71]
	v_mfma_f32_16x16x32_bf16 v[64:67], v[198:201], v[234:237], v[64:67]
	s_setprio 0
	s_barrier
	s_add_i32 s65, s50, s41
	v_lshl_add_u64 v[160:161], s[36:37], 0, v[132:133]
	s_mov_b32 m0, s65
	ds_read_b128 v[202:205], v180 offset:16384
	ds_read_b128 v[210:213], v180 offset:17408
	ds_read_b128 v[214:217], v180 offset:18432
	ds_read_b128 v[218:221], v180 offset:19456
	ds_read_b128 v[222:225], v180 offset:20480
	ds_read_b128 v[226:229], v180 offset:21504
	ds_read_b128 v[230:233], v180 offset:22528
	ds_read_b128 v[234:237], v180 offset:23552
	global_load_lds_dwordx4 v[160:161], off
	s_add_i32 m0, s65, 0x2000
	s_add_u32 s66, s36, 0x80000
	v_lshl_add_u64 v[206:207], s[36:37], 0, v[136:137]
	s_addc_u32 s67, s37, 0
	s_add_i32 s65, s51, s41
	global_load_lds_dwordx4 v[206:207], off
	v_lshl_add_u64 v[238:239], s[66:67], 0, v[132:133]
	s_mov_b32 m0, s65
	v_lshl_add_u64 v[240:241], s[38:39], 0, v[134:135]
	global_load_lds_dwordx4 v[238:239], off
	v_lshl_add_u64 v[238:239], s[66:67], 0, v[136:137]
	s_add_i32 m0, s65, 0x2000
	s_nop 0
	global_load_lds_dwordx4 v[238:239], off
	v_lshl_add_u64 v[238:239], s[38:39], 0, v[130:131]
	s_mov_b32 m0, s31
	s_nop 0
	global_load_lds_dwordx4 v[238:239], off
	s_mov_b32 m0, s42
	s_nop 0
	global_load_lds_dwordx4 v[240:241], off
	s_waitcnt vmcnt(8)
	s_waitcnt lgkmcnt(0)
	s_barrier
	s_setprio 1
	s_waitcnt lgkmcnt(0)
	v_mfma_f32_16x16x32_bf16 v[60:63], v[148:151], v[202:205], v[60:63]
	v_mfma_f32_16x16x32_bf16 v[56:59], v[156:159], v[202:205], v[56:59]
	v_mfma_f32_16x16x32_bf16 v[44:47], v[148:151], v[214:217], v[44:47]
	v_mfma_f32_16x16x32_bf16 v[40:43], v[156:159], v[214:217], v[40:43]
	v_mfma_f32_16x16x32_bf16 v[28:31], v[148:151], v[222:225], v[28:31]
	v_mfma_f32_16x16x32_bf16 v[24:27], v[156:159], v[222:225], v[24:27]
	v_mfma_f32_16x16x32_bf16 v[12:15], v[148:151], v[230:233], v[12:15]
	v_mfma_f32_16x16x32_bf16 v[8:11], v[156:159], v[230:233], v[8:11]
	v_mfma_f32_16x16x32_bf16 v[60:63], v[152:155], v[210:213], v[60:63]
	v_mfma_f32_16x16x32_bf16 v[56:59], v[182:185], v[210:213], v[56:59]
	v_mfma_f32_16x16x32_bf16 v[44:47], v[152:155], v[218:221], v[44:47]
	v_mfma_f32_16x16x32_bf16 v[40:43], v[182:185], v[218:221], v[40:43]
	v_mfma_f32_16x16x32_bf16 v[28:31], v[152:155], v[226:229], v[28:31]
	v_mfma_f32_16x16x32_bf16 v[24:27], v[182:185], v[226:229], v[24:27]
	v_mfma_f32_16x16x32_bf16 v[12:15], v[152:155], v[234:237], v[12:15]
	v_mfma_f32_16x16x32_bf16 v[8:11], v[182:185], v[234:237], v[8:11]
	v_mfma_f32_16x16x32_bf16 v[52:55], v[186:189], v[202:205], v[52:55]
	v_mfma_f32_16x16x32_bf16 v[48:51], v[194:197], v[202:205], v[48:51]
	v_mfma_f32_16x16x32_bf16 v[36:39], v[186:189], v[214:217], v[36:39]
	v_mfma_f32_16x16x32_bf16 v[32:35], v[194:197], v[214:217], v[32:35]
	v_mfma_f32_16x16x32_bf16 v[20:23], v[186:189], v[222:225], v[20:23]
	v_mfma_f32_16x16x32_bf16 v[16:19], v[194:197], v[222:225], v[16:19]
	v_mfma_f32_16x16x32_bf16 v[4:7], v[186:189], v[230:233], v[4:7]
	v_mfma_f32_16x16x32_bf16 v[0:3], v[194:197], v[230:233], v[0:3]
	v_mfma_f32_16x16x32_bf16 v[52:55], v[190:193], v[210:213], v[52:55]
	v_mfma_f32_16x16x32_bf16 v[48:51], v[198:201], v[210:213], v[48:51]
	v_mfma_f32_16x16x32_bf16 v[36:39], v[190:193], v[218:221], v[36:39]
	v_mfma_f32_16x16x32_bf16 v[32:35], v[198:201], v[218:221], v[32:35]
	v_mfma_f32_16x16x32_bf16 v[20:23], v[190:193], v[226:229], v[20:23]
	v_mfma_f32_16x16x32_bf16 v[16:19], v[198:201], v[226:229], v[16:19]
	v_mfma_f32_16x16x32_bf16 v[4:7], v[190:193], v[234:237], v[4:7]
	v_mfma_f32_16x16x32_bf16 v[0:3], v[198:201], v[234:237], v[0:3]
	s_setprio 0
	s_barrier
	s_add_i32 s65, 0, 0x18000
	v_add_u32_e32 v138, s65, v166
	s_add_i32 s66, 0, 0x1c000
	ds_read_b128 v[148:151], v138
	ds_read_b128 v[152:155], v138 offset:1024
	ds_read_b128 v[156:159], v138 offset:2048
	ds_read_b128 v[182:185], v138 offset:3072
	v_add_u32_e32 v138, s66, v166
	ds_read_b128 v[186:189], v138
	ds_read_b128 v[190:193], v138 offset:1024
	ds_read_b128 v[194:197], v138 offset:2048
	ds_read_b128 v[198:201], v138 offset:3072
	s_add_u32 s38, s38, 0x80000
	s_addc_u32 s39, s39, 0
	s_mov_b32 m0, s43
	v_lshl_add_u64 v[242:243], s[38:39], 0, v[130:131]
	ds_read_b128 v[202:205], v180 offset:32768
	ds_read_b128 v[210:213], v180 offset:33792
	ds_read_b128 v[214:217], v180 offset:34816
	ds_read_b128 v[218:221], v180 offset:35840
	ds_read_b128 v[222:225], v180 offset:36864
	ds_read_b128 v[226:229], v180 offset:37888
	ds_read_b128 v[230:233], v180 offset:38912
	ds_read_b128 v[234:237], v180 offset:39936
	global_load_lds_dwordx4 v[242:243], off
	v_lshl_add_u64 v[242:243], s[38:39], 0, v[134:135]
	s_mov_b32 m0, s44
	s_nop 0
	global_load_lds_dwordx4 v[242:243], off
	s_waitcnt vmcnt(8)
	s_waitcnt lgkmcnt(0)
	s_barrier
	s_setprio 1
	s_waitcnt lgkmcnt(0)
	v_mfma_f32_16x16x32_bf16 v[124:127], v[148:151], v[202:205], v[124:127]
	v_mfma_f32_16x16x32_bf16 v[120:123], v[156:159], v[202:205], v[120:123]
	v_mfma_f32_16x16x32_bf16 v[108:111], v[148:151], v[214:217], v[108:111]
	v_mfma_f32_16x16x32_bf16 v[104:107], v[156:159], v[214:217], v[104:107]
	v_mfma_f32_16x16x32_bf16 v[92:95], v[148:151], v[222:225], v[92:95]
	v_mfma_f32_16x16x32_bf16 v[88:91], v[156:159], v[222:225], v[88:91]
	v_mfma_f32_16x16x32_bf16 v[76:79], v[148:151], v[230:233], v[76:79]
	v_mfma_f32_16x16x32_bf16 v[72:75], v[156:159], v[230:233], v[72:75]
	v_mfma_f32_16x16x32_bf16 v[124:127], v[152:155], v[210:213], v[124:127]
	v_mfma_f32_16x16x32_bf16 v[120:123], v[182:185], v[210:213], v[120:123]
	v_mfma_f32_16x16x32_bf16 v[108:111], v[152:155], v[218:221], v[108:111]
	v_mfma_f32_16x16x32_bf16 v[104:107], v[182:185], v[218:221], v[104:107]
	v_mfma_f32_16x16x32_bf16 v[92:95], v[152:155], v[226:229], v[92:95]
	v_mfma_f32_16x16x32_bf16 v[88:91], v[182:185], v[226:229], v[88:91]
	v_mfma_f32_16x16x32_bf16 v[76:79], v[152:155], v[234:237], v[76:79]
	v_mfma_f32_16x16x32_bf16 v[72:75], v[182:185], v[234:237], v[72:75]
	v_mfma_f32_16x16x32_bf16 v[116:119], v[186:189], v[202:205], v[116:119]
	v_mfma_f32_16x16x32_bf16 v[112:115], v[194:197], v[202:205], v[112:115]
	v_mfma_f32_16x16x32_bf16 v[100:103], v[186:189], v[214:217], v[100:103]
	v_mfma_f32_16x16x32_bf16 v[96:99], v[194:197], v[214:217], v[96:99]
	v_mfma_f32_16x16x32_bf16 v[84:87], v[186:189], v[222:225], v[84:87]
	v_mfma_f32_16x16x32_bf16 v[80:83], v[194:197], v[222:225], v[80:83]
	v_mfma_f32_16x16x32_bf16 v[68:71], v[186:189], v[230:233], v[68:71]
	v_mfma_f32_16x16x32_bf16 v[64:67], v[194:197], v[230:233], v[64:67]
	v_mfma_f32_16x16x32_bf16 v[116:119], v[190:193], v[210:213], v[116:119]
	v_mfma_f32_16x16x32_bf16 v[112:115], v[198:201], v[210:213], v[112:115]
	v_mfma_f32_16x16x32_bf16 v[100:103], v[190:193], v[218:221], v[100:103]
	v_mfma_f32_16x16x32_bf16 v[96:99], v[198:201], v[218:221], v[96:99]
	v_mfma_f32_16x16x32_bf16 v[84:87], v[190:193], v[226:229], v[84:87]
	v_mfma_f32_16x16x32_bf16 v[80:83], v[198:201], v[226:229], v[80:83]
	v_mfma_f32_16x16x32_bf16 v[68:71], v[190:193], v[234:237], v[68:71]
	v_mfma_f32_16x16x32_bf16 v[64:67], v[198:201], v[234:237], v[64:67]
	s_setprio 0
	s_barrier
	s_add_i32 s38, s65, s41
	v_lshl_add_u64 v[160:161], v[160:161], 0, s[18:19]
	s_mov_b32 m0, s38
	ds_read_b128 v[202:205], v180 offset:49152
	ds_read_b128 v[210:213], v180 offset:50176
	ds_read_b128 v[214:217], v180 offset:51200
	ds_read_b128 v[218:221], v180 offset:52224
	ds_read_b128 v[222:225], v180 offset:53248
	ds_read_b128 v[226:229], v180 offset:54272
	ds_read_b128 v[230:233], v180 offset:55296
	ds_read_b128 v[234:237], v180 offset:56320
	global_load_lds_dwordx4 v[160:161], off
	s_add_i32 m0, s38, 0x2000
	s_add_u32 s36, s36, 0x80080
	v_lshl_add_u64 v[160:161], v[206:207], 0, s[18:19]
	s_addc_u32 s37, s37, 0
	s_add_i32 s38, s66, s41
	global_load_lds_dwordx4 v[160:161], off
	v_lshl_add_u64 v[160:161], s[36:37], 0, v[132:133]
	s_mov_b32 m0, s38
	s_nop 0
	global_load_lds_dwordx4 v[160:161], off
	v_lshl_add_u64 v[160:161], s[36:37], 0, v[136:137]
	s_add_i32 m0, s38, 0x2000
	s_nop 0
	global_load_lds_dwordx4 v[160:161], off
	v_lshl_add_u64 v[160:161], v[238:239], 0, s[18:19]
	s_mov_b32 m0, s45
	s_nop 0
	global_load_lds_dwordx4 v[160:161], off
	v_lshl_add_u64 v[160:161], v[240:241], 0, s[18:19]
	s_mov_b32 m0, s46
	s_nop 0
	global_load_lds_dwordx4 v[160:161], off
	s_waitcnt vmcnt(8)
	s_waitcnt lgkmcnt(0)
	s_barrier
	s_setprio 1
	s_waitcnt lgkmcnt(0)
	v_mfma_f32_16x16x32_bf16 v[60:63], v[148:151], v[202:205], v[60:63]
	v_mfma_f32_16x16x32_bf16 v[56:59], v[156:159], v[202:205], v[56:59]
	v_mfma_f32_16x16x32_bf16 v[44:47], v[148:151], v[214:217], v[44:47]
	v_mfma_f32_16x16x32_bf16 v[40:43], v[156:159], v[214:217], v[40:43]
	v_mfma_f32_16x16x32_bf16 v[28:31], v[148:151], v[222:225], v[28:31]
	v_mfma_f32_16x16x32_bf16 v[24:27], v[156:159], v[222:225], v[24:27]
	v_mfma_f32_16x16x32_bf16 v[12:15], v[148:151], v[230:233], v[12:15]
	v_mfma_f32_16x16x32_bf16 v[8:11], v[156:159], v[230:233], v[8:11]
	v_mfma_f32_16x16x32_bf16 v[60:63], v[152:155], v[210:213], v[60:63]
	v_mfma_f32_16x16x32_bf16 v[56:59], v[182:185], v[210:213], v[56:59]
	v_mfma_f32_16x16x32_bf16 v[44:47], v[152:155], v[218:221], v[44:47]
	v_mfma_f32_16x16x32_bf16 v[40:43], v[182:185], v[218:221], v[40:43]
	v_mfma_f32_16x16x32_bf16 v[28:31], v[152:155], v[226:229], v[28:31]
	v_mfma_f32_16x16x32_bf16 v[24:27], v[182:185], v[226:229], v[24:27]
	v_mfma_f32_16x16x32_bf16 v[12:15], v[152:155], v[234:237], v[12:15]
	v_mfma_f32_16x16x32_bf16 v[8:11], v[182:185], v[234:237], v[8:11]
	v_mfma_f32_16x16x32_bf16 v[52:55], v[186:189], v[202:205], v[52:55]
	v_mfma_f32_16x16x32_bf16 v[48:51], v[194:197], v[202:205], v[48:51]
	v_mfma_f32_16x16x32_bf16 v[36:39], v[186:189], v[214:217], v[36:39]
	v_mfma_f32_16x16x32_bf16 v[32:35], v[194:197], v[214:217], v[32:35]
	v_mfma_f32_16x16x32_bf16 v[20:23], v[186:189], v[222:225], v[20:23]
	v_mfma_f32_16x16x32_bf16 v[16:19], v[194:197], v[222:225], v[16:19]
	v_mfma_f32_16x16x32_bf16 v[4:7], v[186:189], v[230:233], v[4:7]
	v_mfma_f32_16x16x32_bf16 v[0:3], v[194:197], v[230:233], v[0:3]
	v_mfma_f32_16x16x32_bf16 v[52:55], v[190:193], v[210:213], v[52:55]
	v_mfma_f32_16x16x32_bf16 v[48:51], v[198:201], v[210:213], v[48:51]
	v_mfma_f32_16x16x32_bf16 v[36:39], v[190:193], v[218:221], v[36:39]
	v_mfma_f32_16x16x32_bf16 v[32:35], v[198:201], v[218:221], v[32:35]
	v_mfma_f32_16x16x32_bf16 v[20:23], v[190:193], v[226:229], v[20:23]
	v_mfma_f32_16x16x32_bf16 v[16:19], v[198:201], v[226:229], v[16:19]
	v_mfma_f32_16x16x32_bf16 v[4:7], v[190:193], v[234:237], v[4:7]
	v_mfma_f32_16x16x32_bf16 v[0:3], v[198:201], v[234:237], v[0:3]
	s_setprio 0
	s_barrier
	s_add_i32 s64, s64, 2
	s_add_u32 s34, s34, 0x100
	s_addc_u32 s35, s35, 0
	s_add_u32 s25, s25, 0x100
	s_addc_u32 s63, s63, 0
	s_cmp_gt_u32 s64, 29
	s_cbranch_scc0 .LBB0_163
	s_and_b64 vcc, exec, s[20:21]
	s_cbranch_vccz .LBB0_166
	s_barrier

.LBB0_321:
	s_add_u32 s29, s34, s27
	s_addc_u32 s31, s35, 0
	s_add_u32 s41, s29, 0x100
	s_addc_u32 s48, s31, 0
	s_and_b64 s[46:47], s[44:45], exec
	s_cselect_b32 s49, s37, s48
	s_cselect_b32 s48, s36, s41
	s_add_u32 s27, s24, s27
	s_addc_u32 s41, s25, 0
	s_add_u32 s27, s27, 0x100
	s_addc_u32 s41, s41, 0
	s_and_b64 s[44:45], s[44:45], exec
	s_cselect_b32 s51, s39, s41
	s_cselect_b32 s50, s38, s27
	s_add_u32 s54, s29, 0x80080
	s_addc_u32 s55, s31, 0
	s_add_i32 s74, s66, s2
	ds_read_b128 v[144:147], v129
	ds_read_b128 v[148:151], v129 offset:1024
	ds_read_b128 v[152:155], v129 offset:2048
	ds_read_b128 v[156:159], v129 offset:3072
	ds_read_b128 v[164:167], v141
	ds_read_b128 v[168:171], v141 offset:1024
	ds_read_b128 v[172:175], v141 offset:2048
	ds_read_b128 v[180:183], v141 offset:3072
	s_add_i32 m0, s3, 0xc000
	s_add_i32 s75, s3, 0xe000
	s_add_i32 s71, s74, 0x2000
	s_add_u32 s52, s50, 0x80000
	s_addc_u32 s53, s51, 0
	s_add_i32 s73, s67, s2
	s_add_i32 s72, s73, 0x2000
	s_add_i32 s70, 0, 0x18000
	s_add_i32 s69, 0, 0x1c000
	s_add_u32 s46, s48, 0x80000
	s_addc_u32 s47, s49, 0
	s_add_i32 s41, s70, s2
	s_add_i32 s29, s41, 0x2000
	s_add_u32 s44, s50, 0x80080
	s_addc_u32 s45, s51, 0
	s_add_i32 s31, s69, s2
	s_add_i32 s27, s31, 0x2000
	v_lshl_add_u64 v[160:161], s[54:55], 0, v[130:131]
	ds_read_b128 v[184:187], v142
	ds_read_b128 v[188:191], v142 offset:1024
	ds_read_b128 v[192:195], v142 offset:2048
	ds_read_b128 v[196:199], v142 offset:3072
	ds_read_b128 v[200:203], v142 offset:4096
	ds_read_b128 v[204:207], v142 offset:5120
	ds_read_b128 v[210:213], v142 offset:6144
	ds_read_b128 v[214:217], v142 offset:7168
	global_load_lds_dwordx4 v[160:161], off
	v_lshl_add_u64 v[160:161], s[54:55], 0, v[134:135]
	s_mov_b32 m0, s75
	s_nop 0
	global_load_lds_dwordx4 v[160:161], off
	s_waitcnt vmcnt(8)
	s_waitcnt lgkmcnt(0)
	s_barrier
	s_setprio 1
	s_waitcnt lgkmcnt(0)
	v_mfma_f32_16x16x32_bf16 v[124:127], v[144:147], v[184:187], v[124:127]
	v_mfma_f32_16x16x32_bf16 v[120:123], v[152:155], v[184:187], v[120:123]
	v_mfma_f32_16x16x32_bf16 v[116:119], v[144:147], v[192:195], v[116:119]
	v_mfma_f32_16x16x32_bf16 v[112:115], v[152:155], v[192:195], v[112:115]
	v_mfma_f32_16x16x32_bf16 v[108:111], v[144:147], v[200:203], v[108:111]
	v_mfma_f32_16x16x32_bf16 v[104:107], v[152:155], v[200:203], v[104:107]
	v_mfma_f32_16x16x32_bf16 v[100:103], v[144:147], v[210:213], v[100:103]
	v_mfma_f32_16x16x32_bf16 v[96:99], v[152:155], v[210:213], v[96:99]
	v_mfma_f32_16x16x32_bf16 v[124:127], v[148:151], v[188:191], v[124:127]
	v_mfma_f32_16x16x32_bf16 v[120:123], v[156:159], v[188:191], v[120:123]
	v_mfma_f32_16x16x32_bf16 v[116:119], v[148:151], v[196:199], v[116:119]
	v_mfma_f32_16x16x32_bf16 v[112:115], v[156:159], v[196:199], v[112:115]
	v_mfma_f32_16x16x32_bf16 v[108:111], v[148:151], v[204:207], v[108:111]
	v_mfma_f32_16x16x32_bf16 v[104:107], v[156:159], v[204:207], v[104:107]
	v_mfma_f32_16x16x32_bf16 v[100:103], v[148:151], v[214:217], v[100:103]
	v_mfma_f32_16x16x32_bf16 v[96:99], v[156:159], v[214:217], v[96:99]
	v_mfma_f32_16x16x32_bf16 v[92:95], v[164:167], v[184:187], v[92:95]
	v_mfma_f32_16x16x32_bf16 v[88:91], v[172:175], v[184:187], v[88:91]
	v_mfma_f32_16x16x32_bf16 v[84:87], v[164:167], v[192:195], v[84:87]
	v_mfma_f32_16x16x32_bf16 v[80:83], v[172:175], v[192:195], v[80:83]
	v_mfma_f32_16x16x32_bf16 v[76:79], v[164:167], v[200:203], v[76:79]
	v_mfma_f32_16x16x32_bf16 v[72:75], v[172:175], v[200:203], v[72:75]
	v_mfma_f32_16x16x32_bf16 v[68:71], v[164:167], v[210:213], v[68:71]
	v_mfma_f32_16x16x32_bf16 v[64:67], v[172:175], v[210:213], v[64:67]
	v_mfma_f32_16x16x32_bf16 v[92:95], v[168:171], v[188:191], v[92:95]
	v_mfma_f32_16x16x32_bf16 v[88:91], v[180:183], v[188:191], v[88:91]
	v_mfma_f32_16x16x32_bf16 v[84:87], v[168:171], v[196:199], v[84:87]
	v_mfma_f32_16x16x32_bf16 v[80:83], v[180:183], v[196:199], v[80:83]
	v_mfma_f32_16x16x32_bf16 v[76:79], v[168:171], v[204:207], v[76:79]
	v_mfma_f32_16x16x32_bf16 v[72:75], v[180:183], v[204:207], v[72:75]
	v_mfma_f32_16x16x32_bf16 v[68:71], v[168:171], v[214:217], v[68:71]
	v_mfma_f32_16x16x32_bf16 v[64:67], v[180:183], v[214:217], v[64:67]
	s_setprio 0
	s_barrier
	s_mov_b32 m0, s74
	v_lshl_add_u64 v[160:161], s[50:51], 0, v[132:133]
	ds_read_b128 v[184:187], v142 offset:16384
	ds_read_b128 v[188:191], v142 offset:17408
	ds_read_b128 v[192:195], v142 offset:18432
	ds_read_b128 v[196:199], v142 offset:19456
	ds_read_b128 v[200:203], v142 offset:20480
	ds_read_b128 v[204:207], v142 offset:21504
	ds_read_b128 v[210:213], v142 offset:22528
	ds_read_b128 v[214:217], v142 offset:23552
	global_load_lds_dwordx4 v[160:161], off
	v_lshl_add_u64 v[176:177], s[50:51], 0, v[136:137]
	s_mov_b32 m0, s71
	v_lshl_add_u64 v[218:219], s[52:53], 0, v[132:133]
	global_load_lds_dwordx4 v[176:177], off
	s_mov_b32 m0, s73
	v_lshl_add_u64 v[220:221], s[48:49], 0, v[134:135]
	global_load_lds_dwordx4 v[218:219], off
	v_lshl_add_u64 v[218:219], s[52:53], 0, v[136:137]
	s_mov_b32 m0, s72
	s_nop 0
	global_load_lds_dwordx4 v[218:219], off
	v_lshl_add_u64 v[218:219], s[48:49], 0, v[130:131]
	s_mov_b32 m0, s3
	s_nop 0
	global_load_lds_dwordx4 v[218:219], off
	s_mov_b32 m0, s60
	s_nop 0
	global_load_lds_dwordx4 v[220:221], off
	s_waitcnt vmcnt(8)
	s_waitcnt lgkmcnt(0)
	s_barrier
	s_setprio 1
	s_waitcnt lgkmcnt(0)
	v_mfma_f32_16x16x32_bf16 v[60:63], v[144:147], v[184:187], v[60:63]
	v_mfma_f32_16x16x32_bf16 v[56:59], v[152:155], v[184:187], v[56:59]
	v_mfma_f32_16x16x32_bf16 v[52:55], v[144:147], v[192:195], v[52:55]
	v_mfma_f32_16x16x32_bf16 v[48:51], v[152:155], v[192:195], v[48:51]
	v_mfma_f32_16x16x32_bf16 v[44:47], v[144:147], v[200:203], v[44:47]
	v_mfma_f32_16x16x32_bf16 v[40:43], v[152:155], v[200:203], v[40:43]
	v_mfma_f32_16x16x32_bf16 v[36:39], v[144:147], v[210:213], v[36:39]
	v_mfma_f32_16x16x32_bf16 v[32:35], v[152:155], v[210:213], v[32:35]
	v_mfma_f32_16x16x32_bf16 v[60:63], v[148:151], v[188:191], v[60:63]
	v_mfma_f32_16x16x32_bf16 v[56:59], v[156:159], v[188:191], v[56:59]
	v_mfma_f32_16x16x32_bf16 v[52:55], v[148:151], v[196:199], v[52:55]
	v_mfma_f32_16x16x32_bf16 v[48:51], v[156:159], v[196:199], v[48:51]
	v_mfma_f32_16x16x32_bf16 v[44:47], v[148:151], v[204:207], v[44:47]
	v_mfma_f32_16x16x32_bf16 v[40:43], v[156:159], v[204:207], v[40:43]
	v_mfma_f32_16x16x32_bf16 v[36:39], v[148:151], v[214:217], v[36:39]
	v_mfma_f32_16x16x32_bf16 v[32:35], v[156:159], v[214:217], v[32:35]
	v_mfma_f32_16x16x32_bf16 v[28:31], v[164:167], v[184:187], v[28:31]
	v_mfma_f32_16x16x32_bf16 v[24:27], v[172:175], v[184:187], v[24:27]
	v_mfma_f32_16x16x32_bf16 v[20:23], v[164:167], v[192:195], v[20:23]
	v_mfma_f32_16x16x32_bf16 v[16:19], v[172:175], v[192:195], v[16:19]
	v_mfma_f32_16x16x32_bf16 v[12:15], v[164:167], v[200:203], v[12:15]
	v_mfma_f32_16x16x32_bf16 v[8:11], v[172:175], v[200:203], v[8:11]
	v_mfma_f32_16x16x32_bf16 v[4:7], v[164:167], v[210:213], v[4:7]
	v_mfma_f32_16x16x32_bf16 v[0:3], v[172:175], v[210:213], v[0:3]
	v_mfma_f32_16x16x32_bf16 v[28:31], v[168:171], v[188:191], v[28:31]
	v_mfma_f32_16x16x32_bf16 v[24:27], v[180:183], v[188:191], v[24:27]
	v_mfma_f32_16x16x32_bf16 v[20:23], v[168:171], v[196:199], v[20:23]
	v_mfma_f32_16x16x32_bf16 v[16:19], v[180:183], v[196:199], v[16:19]
	v_mfma_f32_16x16x32_bf16 v[12:15], v[168:171], v[204:207], v[12:15]
	v_mfma_f32_16x16x32_bf16 v[8:11], v[180:183], v[204:207], v[8:11]
	v_mfma_f32_16x16x32_bf16 v[4:7], v[168:171], v[214:217], v[4:7]
	v_mfma_f32_16x16x32_bf16 v[0:3], v[180:183], v[214:217], v[0:3]
	s_setprio 0
	s_barrier
	v_add_u32_e32 v143, s70, v140
	ds_read_b128 v[144:147], v143
	ds_read_b128 v[148:151], v143 offset:1024
	ds_read_b128 v[152:155], v143 offset:2048
	ds_read_b128 v[156:159], v143 offset:3072
	v_add_u32_e32 v143, s69, v140
	ds_read_b128 v[164:167], v143
	ds_read_b128 v[168:171], v143 offset:1024
	ds_read_b128 v[172:175], v143 offset:2048
	ds_read_b128 v[180:183], v143 offset:3072
	s_mov_b32 m0, s61
	v_lshl_add_u64 v[222:223], s[46:47], 0, v[130:131]
	ds_read_b128 v[184:187], v142 offset:32768
	ds_read_b128 v[188:191], v142 offset:33792
	ds_read_b128 v[192:195], v142 offset:34816
	ds_read_b128 v[196:199], v142 offset:35840
	ds_read_b128 v[200:203], v142 offset:36864
	ds_read_b128 v[204:207], v142 offset:37888
	ds_read_b128 v[210:213], v142 offset:38912
	ds_read_b128 v[214:217], v142 offset:39936
	global_load_lds_dwordx4 v[222:223], off
	v_lshl_add_u64 v[222:223], s[46:47], 0, v[134:135]
	s_mov_b32 m0, s62
	s_nop 0
	global_load_lds_dwordx4 v[222:223], off
	s_waitcnt vmcnt(8)
	s_waitcnt lgkmcnt(0)
	s_barrier
	s_setprio 1
	s_waitcnt lgkmcnt(0)
	v_mfma_f32_16x16x32_bf16 v[124:127], v[144:147], v[184:187], v[124:127]
	v_mfma_f32_16x16x32_bf16 v[120:123], v[152:155], v[184:187], v[120:123]
	v_mfma_f32_16x16x32_bf16 v[116:119], v[144:147], v[192:195], v[116:119]
	v_mfma_f32_16x16x32_bf16 v[112:115], v[152:155], v[192:195], v[112:115]
	v_mfma_f32_16x16x32_bf16 v[108:111], v[144:147], v[200:203], v[108:111]
	v_mfma_f32_16x16x32_bf16 v[104:107], v[152:155], v[200:203], v[104:107]
	v_mfma_f32_16x16x32_bf16 v[100:103], v[144:147], v[210:213], v[100:103]
	v_mfma_f32_16x16x32_bf16 v[96:99], v[152:155], v[210:213], v[96:99]
	v_mfma_f32_16x16x32_bf16 v[124:127], v[148:151], v[188:191], v[124:127]
	v_mfma_f32_16x16x32_bf16 v[120:123], v[156:159], v[188:191], v[120:123]
	v_mfma_f32_16x16x32_bf16 v[116:119], v[148:151], v[196:199], v[116:119]
	v_mfma_f32_16x16x32_bf16 v[112:115], v[156:159], v[196:199], v[112:115]
	v_mfma_f32_16x16x32_bf16 v[108:111], v[148:151], v[204:207], v[108:111]
	v_mfma_f32_16x16x32_bf16 v[104:107], v[156:159], v[204:207], v[104:107]
	v_mfma_f32_16x16x32_bf16 v[100:103], v[148:151], v[214:217], v[100:103]
	v_mfma_f32_16x16x32_bf16 v[96:99], v[156:159], v[214:217], v[96:99]
	v_mfma_f32_16x16x32_bf16 v[92:95], v[164:167], v[184:187], v[92:95]
	v_mfma_f32_16x16x32_bf16 v[88:91], v[172:175], v[184:187], v[88:91]
	v_mfma_f32_16x16x32_bf16 v[84:87], v[164:167], v[192:195], v[84:87]
	v_mfma_f32_16x16x32_bf16 v[80:83], v[172:175], v[192:195], v[80:83]
	v_mfma_f32_16x16x32_bf16 v[76:79], v[164:167], v[200:203], v[76:79]
	v_mfma_f32_16x16x32_bf16 v[72:75], v[172:175], v[200:203], v[72:75]
	v_mfma_f32_16x16x32_bf16 v[68:71], v[164:167], v[210:213], v[68:71]
	v_mfma_f32_16x16x32_bf16 v[64:67], v[172:175], v[210:213], v[64:67]
	v_mfma_f32_16x16x32_bf16 v[92:95], v[168:171], v[188:191], v[92:95]
	v_mfma_f32_16x16x32_bf16 v[88:91], v[180:183], v[188:191], v[88:91]
	v_mfma_f32_16x16x32_bf16 v[84:87], v[168:171], v[196:199], v[84:87]
	v_mfma_f32_16x16x32_bf16 v[80:83], v[180:183], v[196:199], v[80:83]
	v_mfma_f32_16x16x32_bf16 v[76:79], v[168:171], v[204:207], v[76:79]
	v_mfma_f32_16x16x32_bf16 v[72:75], v[180:183], v[204:207], v[72:75]
	v_mfma_f32_16x16x32_bf16 v[68:71], v[168:171], v[214:217], v[68:71]
	v_mfma_f32_16x16x32_bf16 v[64:67], v[180:183], v[214:217], v[64:67]
	s_setprio 0
	s_barrier
	s_mov_b32 m0, s41
	v_lshl_add_u64 v[160:161], v[160:161], 0, s[20:21]
	ds_read_b128 v[184:187], v142 offset:49152
	ds_read_b128 v[188:191], v142 offset:50176
	ds_read_b128 v[192:195], v142 offset:51200
	ds_read_b128 v[196:199], v142 offset:52224
	ds_read_b128 v[200:203], v142 offset:53248
	ds_read_b128 v[204:207], v142 offset:54272
	ds_read_b128 v[210:213], v142 offset:55296
	ds_read_b128 v[214:217], v142 offset:56320
	global_load_lds_dwordx4 v[160:161], off
	v_lshl_add_u64 v[160:161], v[176:177], 0, s[20:21]
	s_mov_b32 m0, s29
	s_nop 0
	global_load_lds_dwordx4 v[160:161], off
	v_lshl_add_u64 v[160:161], s[44:45], 0, v[132:133]
	s_mov_b32 m0, s31
	s_nop 0
	global_load_lds_dwordx4 v[160:161], off
	v_lshl_add_u64 v[160:161], s[44:45], 0, v[136:137]
	s_mov_b32 m0, s27
	s_nop 0
	global_load_lds_dwordx4 v[160:161], off
	v_lshl_add_u64 v[160:161], v[218:219], 0, s[20:21]
	s_mov_b32 m0, s64
	s_nop 0
	global_load_lds_dwordx4 v[160:161], off
	v_lshl_add_u64 v[160:161], v[220:221], 0, s[20:21]
	s_mov_b32 m0, s65
	s_nop 0
	global_load_lds_dwordx4 v[160:161], off
	s_waitcnt vmcnt(8)
	s_waitcnt lgkmcnt(0)
	s_barrier
	s_setprio 1
	s_waitcnt lgkmcnt(0)
	v_mfma_f32_16x16x32_bf16 v[60:63], v[144:147], v[184:187], v[60:63]
	v_mfma_f32_16x16x32_bf16 v[56:59], v[152:155], v[184:187], v[56:59]
	v_mfma_f32_16x16x32_bf16 v[52:55], v[144:147], v[192:195], v[52:55]
	v_mfma_f32_16x16x32_bf16 v[48:51], v[152:155], v[192:195], v[48:51]
	v_mfma_f32_16x16x32_bf16 v[44:47], v[144:147], v[200:203], v[44:47]
	v_mfma_f32_16x16x32_bf16 v[40:43], v[152:155], v[200:203], v[40:43]
	v_mfma_f32_16x16x32_bf16 v[36:39], v[144:147], v[210:213], v[36:39]
	v_mfma_f32_16x16x32_bf16 v[32:35], v[152:155], v[210:213], v[32:35]
	v_mfma_f32_16x16x32_bf16 v[60:63], v[148:151], v[188:191], v[60:63]
	v_mfma_f32_16x16x32_bf16 v[56:59], v[156:159], v[188:191], v[56:59]
	v_mfma_f32_16x16x32_bf16 v[52:55], v[148:151], v[196:199], v[52:55]
	v_mfma_f32_16x16x32_bf16 v[48:51], v[156:159], v[196:199], v[48:51]
	v_mfma_f32_16x16x32_bf16 v[44:47], v[148:151], v[204:207], v[44:47]
	v_mfma_f32_16x16x32_bf16 v[40:43], v[156:159], v[204:207], v[40:43]
	v_mfma_f32_16x16x32_bf16 v[36:39], v[148:151], v[214:217], v[36:39]
	v_mfma_f32_16x16x32_bf16 v[32:35], v[156:159], v[214:217], v[32:35]
	v_mfma_f32_16x16x32_bf16 v[28:31], v[164:167], v[184:187], v[28:31]
	v_mfma_f32_16x16x32_bf16 v[24:27], v[172:175], v[184:187], v[24:27]
	v_mfma_f32_16x16x32_bf16 v[20:23], v[164:167], v[192:195], v[20:23]
	v_mfma_f32_16x16x32_bf16 v[16:19], v[172:175], v[192:195], v[16:19]
	v_mfma_f32_16x16x32_bf16 v[12:15], v[164:167], v[200:203], v[12:15]
	v_mfma_f32_16x16x32_bf16 v[8:11], v[172:175], v[200:203], v[8:11]
	v_mfma_f32_16x16x32_bf16 v[4:7], v[164:167], v[210:213], v[4:7]
	v_mfma_f32_16x16x32_bf16 v[0:3], v[172:175], v[210:213], v[0:3]
	v_mfma_f32_16x16x32_bf16 v[28:31], v[168:171], v[188:191], v[28:31]
	v_mfma_f32_16x16x32_bf16 v[24:27], v[180:183], v[188:191], v[24:27]
	v_mfma_f32_16x16x32_bf16 v[20:23], v[168:171], v[196:199], v[20:23]
	v_mfma_f32_16x16x32_bf16 v[16:19], v[180:183], v[196:199], v[16:19]
	v_mfma_f32_16x16x32_bf16 v[12:15], v[168:171], v[204:207], v[12:15]
	v_mfma_f32_16x16x32_bf16 v[8:11], v[180:183], v[204:207], v[8:11]
	v_mfma_f32_16x16x32_bf16 v[4:7], v[168:171], v[214:217], v[4:7]
	v_mfma_f32_16x16x32_bf16 v[0:3], v[180:183], v[214:217], v[0:3]
	s_setprio 0
	s_barrier
	s_movk_i32 s27, 0x100
	s_andn2_b64 vcc, exec, s[42:43]
	s_mov_b64 s[44:45], -1
	s_mov_b64 s[42:43], 0
	s_cbranch_vccz .LBB0_321
	s_and_b64 vcc, exec, s[22:23]
	s_cbranch_vccz .LBB0_324
	s_barrier

.LBB0_965:
	ds_read_b128 v[128:131], v169
	ds_read_b128 v[132:135], v169 offset:1024
	ds_read_b128 v[154:157], v169 offset:2048
	ds_read_b128 v[158:161], v169 offset:3072
	ds_read_b128 v[172:175], v170
	ds_read_b128 v[180:183], v170 offset:1024
	ds_read_b128 v[184:187], v170 offset:2048
	ds_read_b128 v[188:191], v170 offset:3072
	s_add_u32 s30, s28, 0xfff80080
	s_addc_u32 s31, s29, -1
	s_cmp_eq_u32 s57, 28
	s_cselect_b32 s35, s2, s31
	s_cselect_b32 s34, s3, s30
	s_cselect_b32 s31, s17, s27
	s_cselect_b32 s30, s19, s25
	v_lshl_add_u64 v[162:163], s[28:29], 0, v[148:149]
	s_add_i32 m0, s38, 0xc000
	ds_read_b128 v[192:195], v171
	ds_read_b128 v[196:199], v171 offset:1024
	ds_read_b128 v[200:203], v171 offset:2048
	ds_read_b128 v[204:207], v171 offset:3072
	ds_read_b128 v[210:213], v171 offset:4096
	ds_read_b128 v[214:217], v171 offset:5120
	ds_read_b128 v[218:221], v171 offset:6144
	ds_read_b128 v[222:225], v171 offset:7168
	global_load_lds_dwordx4 v[162:163], off
	v_lshl_add_u64 v[162:163], s[28:29], 0, v[150:151]
	s_add_i32 m0, s38, 0xe000
	s_nop 0
	global_load_lds_dwordx4 v[162:163], off
	s_waitcnt vmcnt(8)
	s_waitcnt lgkmcnt(0)
	s_barrier
	s_setprio 1
	s_waitcnt lgkmcnt(0)
	v_mfma_f32_16x16x32_bf16 v[124:127], v[128:131], v[192:195], v[124:127]
	v_mfma_f32_16x16x32_bf16 v[120:123], v[154:157], v[192:195], v[120:123]
	v_mfma_f32_16x16x32_bf16 v[108:111], v[128:131], v[200:203], v[108:111]
	v_mfma_f32_16x16x32_bf16 v[104:107], v[154:157], v[200:203], v[104:107]
	v_mfma_f32_16x16x32_bf16 v[92:95], v[128:131], v[210:213], v[92:95]
	v_mfma_f32_16x16x32_bf16 v[88:91], v[154:157], v[210:213], v[88:91]
	v_mfma_f32_16x16x32_bf16 v[76:79], v[128:131], v[218:221], v[76:79]
	v_mfma_f32_16x16x32_bf16 v[72:75], v[154:157], v[218:221], v[72:75]
	v_mfma_f32_16x16x32_bf16 v[124:127], v[132:135], v[196:199], v[124:127]
	v_mfma_f32_16x16x32_bf16 v[120:123], v[158:161], v[196:199], v[120:123]
	v_mfma_f32_16x16x32_bf16 v[108:111], v[132:135], v[204:207], v[108:111]
	v_mfma_f32_16x16x32_bf16 v[104:107], v[158:161], v[204:207], v[104:107]
	v_mfma_f32_16x16x32_bf16 v[92:95], v[132:135], v[214:217], v[92:95]
	v_mfma_f32_16x16x32_bf16 v[88:91], v[158:161], v[214:217], v[88:91]
	v_mfma_f32_16x16x32_bf16 v[76:79], v[132:135], v[222:225], v[76:79]
	v_mfma_f32_16x16x32_bf16 v[72:75], v[158:161], v[222:225], v[72:75]
	v_mfma_f32_16x16x32_bf16 v[116:119], v[172:175], v[192:195], v[116:119]
	v_mfma_f32_16x16x32_bf16 v[112:115], v[184:187], v[192:195], v[112:115]
	v_mfma_f32_16x16x32_bf16 v[100:103], v[172:175], v[200:203], v[100:103]
	v_mfma_f32_16x16x32_bf16 v[96:99], v[184:187], v[200:203], v[96:99]
	v_mfma_f32_16x16x32_bf16 v[84:87], v[172:175], v[210:213], v[84:87]
	v_mfma_f32_16x16x32_bf16 v[80:83], v[184:187], v[210:213], v[80:83]
	v_mfma_f32_16x16x32_bf16 v[68:71], v[172:175], v[218:221], v[68:71]
	v_mfma_f32_16x16x32_bf16 v[64:67], v[184:187], v[218:221], v[64:67]
	v_mfma_f32_16x16x32_bf16 v[116:119], v[180:183], v[196:199], v[116:119]
	v_mfma_f32_16x16x32_bf16 v[112:115], v[188:191], v[196:199], v[112:115]
	v_mfma_f32_16x16x32_bf16 v[100:103], v[180:183], v[204:207], v[100:103]
	v_mfma_f32_16x16x32_bf16 v[96:99], v[188:191], v[204:207], v[96:99]
	v_mfma_f32_16x16x32_bf16 v[84:87], v[180:183], v[214:217], v[84:87]
	v_mfma_f32_16x16x32_bf16 v[80:83], v[188:191], v[214:217], v[80:83]
	v_mfma_f32_16x16x32_bf16 v[68:71], v[180:183], v[222:225], v[68:71]
	v_mfma_f32_16x16x32_bf16 v[64:67], v[188:191], v[222:225], v[64:67]
	s_setprio 0
	s_barrier
	s_add_i32 s58, s47, s37
	v_lshl_add_u64 v[162:163], s[30:31], 0, v[140:141]
	s_mov_b32 m0, s58
	ds_read_b128 v[192:195], v171 offset:16384
	ds_read_b128 v[196:199], v171 offset:17408
	ds_read_b128 v[200:203], v171 offset:18432
	ds_read_b128 v[204:207], v171 offset:19456
	ds_read_b128 v[210:213], v171 offset:20480
	ds_read_b128 v[214:217], v171 offset:21504
	ds_read_b128 v[218:221], v171 offset:22528
	ds_read_b128 v[222:225], v171 offset:23552
	global_load_lds_dwordx4 v[162:163], off
	s_add_i32 m0, s58, 0x2000
	s_add_u32 s58, s30, 0x80000
	v_lshl_add_u64 v[176:177], s[30:31], 0, v[144:145]
	s_addc_u32 s59, s31, 0
	s_add_i32 s60, s48, s37
	global_load_lds_dwordx4 v[176:177], off
	v_lshl_add_u64 v[226:227], s[58:59], 0, v[140:141]
	s_mov_b32 m0, s60
	v_lshl_add_u64 v[228:229], s[34:35], 0, v[142:143]
	global_load_lds_dwordx4 v[226:227], off
	v_lshl_add_u64 v[226:227], s[58:59], 0, v[144:145]
	s_add_i32 m0, s60, 0x2000
	s_nop 0
	global_load_lds_dwordx4 v[226:227], off
	v_lshl_add_u64 v[226:227], s[34:35], 0, v[138:139]
	s_mov_b32 m0, s38
	s_nop 0
	global_load_lds_dwordx4 v[226:227], off
	s_mov_b32 m0, s39
	s_nop 0
	global_load_lds_dwordx4 v[228:229], off
	s_waitcnt vmcnt(8)
	s_waitcnt lgkmcnt(0)
	s_barrier
	s_setprio 1
	s_waitcnt lgkmcnt(0)
	v_mfma_f32_16x16x32_bf16 v[60:63], v[128:131], v[192:195], v[60:63]
	v_mfma_f32_16x16x32_bf16 v[56:59], v[154:157], v[192:195], v[56:59]
	v_mfma_f32_16x16x32_bf16 v[44:47], v[128:131], v[200:203], v[44:47]
	v_mfma_f32_16x16x32_bf16 v[40:43], v[154:157], v[200:203], v[40:43]
	v_mfma_f32_16x16x32_bf16 v[28:31], v[128:131], v[210:213], v[28:31]
	v_mfma_f32_16x16x32_bf16 v[24:27], v[154:157], v[210:213], v[24:27]
	v_mfma_f32_16x16x32_bf16 v[12:15], v[128:131], v[218:221], v[12:15]
	v_mfma_f32_16x16x32_bf16 v[8:11], v[154:157], v[218:221], v[8:11]
	v_mfma_f32_16x16x32_bf16 v[60:63], v[132:135], v[196:199], v[60:63]
	v_mfma_f32_16x16x32_bf16 v[56:59], v[158:161], v[196:199], v[56:59]
	v_mfma_f32_16x16x32_bf16 v[44:47], v[132:135], v[204:207], v[44:47]
	v_mfma_f32_16x16x32_bf16 v[40:43], v[158:161], v[204:207], v[40:43]
	v_mfma_f32_16x16x32_bf16 v[28:31], v[132:135], v[214:217], v[28:31]
	v_mfma_f32_16x16x32_bf16 v[24:27], v[158:161], v[214:217], v[24:27]
	v_mfma_f32_16x16x32_bf16 v[12:15], v[132:135], v[222:225], v[12:15]
	v_mfma_f32_16x16x32_bf16 v[8:11], v[158:161], v[222:225], v[8:11]
	v_mfma_f32_16x16x32_bf16 v[52:55], v[172:175], v[192:195], v[52:55]
	v_mfma_f32_16x16x32_bf16 v[48:51], v[184:187], v[192:195], v[48:51]
	v_mfma_f32_16x16x32_bf16 v[36:39], v[172:175], v[200:203], v[36:39]
	v_mfma_f32_16x16x32_bf16 v[32:35], v[184:187], v[200:203], v[32:35]
	v_mfma_f32_16x16x32_bf16 v[20:23], v[172:175], v[210:213], v[20:23]
	v_mfma_f32_16x16x32_bf16 v[16:19], v[184:187], v[210:213], v[16:19]
	v_mfma_f32_16x16x32_bf16 v[4:7], v[172:175], v[218:221], v[4:7]
	v_mfma_f32_16x16x32_bf16 v[0:3], v[184:187], v[218:221], v[0:3]
	v_mfma_f32_16x16x32_bf16 v[52:55], v[180:183], v[196:199], v[52:55]
	v_mfma_f32_16x16x32_bf16 v[48:51], v[188:191], v[196:199], v[48:51]
	v_mfma_f32_16x16x32_bf16 v[36:39], v[180:183], v[204:207], v[36:39]
	v_mfma_f32_16x16x32_bf16 v[32:35], v[188:191], v[204:207], v[32:35]
	v_mfma_f32_16x16x32_bf16 v[20:23], v[180:183], v[214:217], v[20:23]
	v_mfma_f32_16x16x32_bf16 v[16:19], v[188:191], v[214:217], v[16:19]
	v_mfma_f32_16x16x32_bf16 v[4:7], v[180:183], v[222:225], v[4:7]
	v_mfma_f32_16x16x32_bf16 v[0:3], v[188:191], v[222:225], v[0:3]
	s_setprio 0
	s_barrier
	s_add_i32 s58, 0, 0x18000
	v_add_u32_e32 v146, s58, v167
	s_add_i32 s59, 0, 0x1c000
	ds_read_b128 v[128:131], v146
	ds_read_b128 v[132:135], v146 offset:1024
	ds_read_b128 v[154:157], v146 offset:2048
	ds_read_b128 v[158:161], v146 offset:3072
	v_add_u32_e32 v146, s59, v167
	ds_read_b128 v[172:175], v146
	ds_read_b128 v[180:183], v146 offset:1024
	ds_read_b128 v[184:187], v146 offset:2048
	ds_read_b128 v[188:191], v146 offset:3072
	s_add_u32 s34, s34, 0x80000
	s_addc_u32 s35, s35, 0
	s_mov_b32 m0, s40
	v_lshl_add_u64 v[230:231], s[34:35], 0, v[138:139]
	ds_read_b128 v[192:195], v171 offset:32768
	ds_read_b128 v[196:199], v171 offset:33792
	ds_read_b128 v[200:203], v171 offset:34816
	ds_read_b128 v[204:207], v171 offset:35840
	ds_read_b128 v[210:213], v171 offset:36864
	ds_read_b128 v[214:217], v171 offset:37888
	ds_read_b128 v[218:221], v171 offset:38912
	ds_read_b128 v[222:225], v171 offset:39936
	global_load_lds_dwordx4 v[230:231], off
	v_lshl_add_u64 v[230:231], s[34:35], 0, v[142:143]
	s_mov_b32 m0, s41
	s_nop 0
	global_load_lds_dwordx4 v[230:231], off
	s_waitcnt vmcnt(8)
	s_waitcnt lgkmcnt(0)
	s_barrier
	s_setprio 1
	s_waitcnt lgkmcnt(0)
	v_mfma_f32_16x16x32_bf16 v[124:127], v[128:131], v[192:195], v[124:127]
	v_mfma_f32_16x16x32_bf16 v[120:123], v[154:157], v[192:195], v[120:123]
	v_mfma_f32_16x16x32_bf16 v[108:111], v[128:131], v[200:203], v[108:111]
	v_mfma_f32_16x16x32_bf16 v[104:107], v[154:157], v[200:203], v[104:107]
	v_mfma_f32_16x16x32_bf16 v[92:95], v[128:131], v[210:213], v[92:95]
	v_mfma_f32_16x16x32_bf16 v[88:91], v[154:157], v[210:213], v[88:91]
	v_mfma_f32_16x16x32_bf16 v[76:79], v[128:131], v[218:221], v[76:79]
	v_mfma_f32_16x16x32_bf16 v[72:75], v[154:157], v[218:221], v[72:75]
	v_mfma_f32_16x16x32_bf16 v[124:127], v[132:135], v[196:199], v[124:127]
	v_mfma_f32_16x16x32_bf16 v[120:123], v[158:161], v[196:199], v[120:123]
	v_mfma_f32_16x16x32_bf16 v[108:111], v[132:135], v[204:207], v[108:111]
	v_mfma_f32_16x16x32_bf16 v[104:107], v[158:161], v[204:207], v[104:107]
	v_mfma_f32_16x16x32_bf16 v[92:95], v[132:135], v[214:217], v[92:95]
	v_mfma_f32_16x16x32_bf16 v[88:91], v[158:161], v[214:217], v[88:91]
	v_mfma_f32_16x16x32_bf16 v[76:79], v[132:135], v[222:225], v[76:79]
	v_mfma_f32_16x16x32_bf16 v[72:75], v[158:161], v[222:225], v[72:75]
	v_mfma_f32_16x16x32_bf16 v[116:119], v[172:175], v[192:195], v[116:119]
	v_mfma_f32_16x16x32_bf16 v[112:115], v[184:187], v[192:195], v[112:115]
	v_mfma_f32_16x16x32_bf16 v[100:103], v[172:175], v[200:203], v[100:103]
	v_mfma_f32_16x16x32_bf16 v[96:99], v[184:187], v[200:203], v[96:99]
	v_mfma_f32_16x16x32_bf16 v[84:87], v[172:175], v[210:213], v[84:87]
	v_mfma_f32_16x16x32_bf16 v[80:83], v[184:187], v[210:213], v[80:83]
	v_mfma_f32_16x16x32_bf16 v[68:71], v[172:175], v[218:221], v[68:71]
	v_mfma_f32_16x16x32_bf16 v[64:67], v[184:187], v[218:221], v[64:67]
	v_mfma_f32_16x16x32_bf16 v[116:119], v[180:183], v[196:199], v[116:119]
	v_mfma_f32_16x16x32_bf16 v[112:115], v[188:191], v[196:199], v[112:115]
	v_mfma_f32_16x16x32_bf16 v[100:103], v[180:183], v[204:207], v[100:103]
	v_mfma_f32_16x16x32_bf16 v[96:99], v[188:191], v[204:207], v[96:99]
	v_mfma_f32_16x16x32_bf16 v[84:87], v[180:183], v[214:217], v[84:87]
	v_mfma_f32_16x16x32_bf16 v[80:83], v[188:191], v[214:217], v[80:83]
	v_mfma_f32_16x16x32_bf16 v[68:71], v[180:183], v[222:225], v[68:71]
	v_mfma_f32_16x16x32_bf16 v[64:67], v[188:191], v[222:225], v[64:67]
	s_setprio 0
	s_barrier
	s_add_i32 s34, s58, s37
	v_lshl_add_u64 v[162:163], v[162:163], 0, s[12:13]
	s_mov_b32 m0, s34
	ds_read_b128 v[192:195], v171 offset:49152
	ds_read_b128 v[196:199], v171 offset:50176
	ds_read_b128 v[200:203], v171 offset:51200
	ds_read_b128 v[204:207], v171 offset:52224
	ds_read_b128 v[210:213], v171 offset:53248
	ds_read_b128 v[214:217], v171 offset:54272
	ds_read_b128 v[218:221], v171 offset:55296
	ds_read_b128 v[222:225], v171 offset:56320
	global_load_lds_dwordx4 v[162:163], off
	s_add_i32 m0, s34, 0x2000
	s_add_u32 s30, s30, 0x80080
	v_lshl_add_u64 v[162:163], v[176:177], 0, s[12:13]
	s_addc_u32 s31, s31, 0
	s_add_i32 s34, s59, s37
	global_load_lds_dwordx4 v[162:163], off
	v_lshl_add_u64 v[162:163], s[30:31], 0, v[140:141]
	s_mov_b32 m0, s34
	s_nop 0
	global_load_lds_dwordx4 v[162:163], off
	v_lshl_add_u64 v[162:163], s[30:31], 0, v[144:145]
	s_add_i32 m0, s34, 0x2000
	s_nop 0
	global_load_lds_dwordx4 v[162:163], off
	v_lshl_add_u64 v[162:163], v[226:227], 0, s[12:13]
	s_mov_b32 m0, s43
	s_nop 0
	global_load_lds_dwordx4 v[162:163], off
	v_lshl_add_u64 v[162:163], v[228:229], 0, s[12:13]
	s_mov_b32 m0, s44
	s_nop 0
	global_load_lds_dwordx4 v[162:163], off
	s_waitcnt vmcnt(8)
	s_waitcnt lgkmcnt(0)
	s_barrier
	s_setprio 1
	s_waitcnt lgkmcnt(0)
	v_mfma_f32_16x16x32_bf16 v[60:63], v[128:131], v[192:195], v[60:63]
	v_mfma_f32_16x16x32_bf16 v[56:59], v[154:157], v[192:195], v[56:59]
	v_mfma_f32_16x16x32_bf16 v[44:47], v[128:131], v[200:203], v[44:47]
	v_mfma_f32_16x16x32_bf16 v[40:43], v[154:157], v[200:203], v[40:43]
	v_mfma_f32_16x16x32_bf16 v[28:31], v[128:131], v[210:213], v[28:31]
	v_mfma_f32_16x16x32_bf16 v[24:27], v[154:157], v[210:213], v[24:27]
	v_mfma_f32_16x16x32_bf16 v[12:15], v[128:131], v[218:221], v[12:15]
	v_mfma_f32_16x16x32_bf16 v[8:11], v[154:157], v[218:221], v[8:11]
	v_mfma_f32_16x16x32_bf16 v[60:63], v[132:135], v[196:199], v[60:63]
	v_mfma_f32_16x16x32_bf16 v[56:59], v[158:161], v[196:199], v[56:59]
	v_mfma_f32_16x16x32_bf16 v[44:47], v[132:135], v[204:207], v[44:47]
	v_mfma_f32_16x16x32_bf16 v[40:43], v[158:161], v[204:207], v[40:43]
	v_mfma_f32_16x16x32_bf16 v[28:31], v[132:135], v[214:217], v[28:31]
	v_mfma_f32_16x16x32_bf16 v[24:27], v[158:161], v[214:217], v[24:27]
	v_mfma_f32_16x16x32_bf16 v[12:15], v[132:135], v[222:225], v[12:15]
	v_mfma_f32_16x16x32_bf16 v[8:11], v[158:161], v[222:225], v[8:11]
	v_mfma_f32_16x16x32_bf16 v[52:55], v[172:175], v[192:195], v[52:55]
	v_mfma_f32_16x16x32_bf16 v[48:51], v[184:187], v[192:195], v[48:51]
	v_mfma_f32_16x16x32_bf16 v[36:39], v[172:175], v[200:203], v[36:39]
	v_mfma_f32_16x16x32_bf16 v[32:35], v[184:187], v[200:203], v[32:35]
	v_mfma_f32_16x16x32_bf16 v[20:23], v[172:175], v[210:213], v[20:23]
	v_mfma_f32_16x16x32_bf16 v[16:19], v[184:187], v[210:213], v[16:19]
	v_mfma_f32_16x16x32_bf16 v[4:7], v[172:175], v[218:221], v[4:7]
	v_mfma_f32_16x16x32_bf16 v[0:3], v[184:187], v[218:221], v[0:3]
	v_mfma_f32_16x16x32_bf16 v[52:55], v[180:183], v[196:199], v[52:55]
	v_mfma_f32_16x16x32_bf16 v[48:51], v[188:191], v[196:199], v[48:51]
	v_mfma_f32_16x16x32_bf16 v[36:39], v[180:183], v[204:207], v[36:39]
	v_mfma_f32_16x16x32_bf16 v[32:35], v[188:191], v[204:207], v[32:35]
	v_mfma_f32_16x16x32_bf16 v[20:23], v[180:183], v[214:217], v[20:23]
	v_mfma_f32_16x16x32_bf16 v[16:19], v[188:191], v[214:217], v[16:19]
	v_mfma_f32_16x16x32_bf16 v[4:7], v[180:183], v[222:225], v[4:7]
	v_mfma_f32_16x16x32_bf16 v[0:3], v[188:191], v[222:225], v[0:3]
	s_setprio 0
	s_barrier
	s_add_i32 s57, s57, 2
	s_add_u32 s28, s28, 0x100
	s_addc_u32 s29, s29, 0
	s_add_u32 s25, s25, 0x100
	s_addc_u32 s27, s27, 0
	s_cmp_gt_u32 s57, 29
	s_cbranch_scc0 .LBB0_965
	s_and_b64 vcc, exec, s[14:15]
	s_cbranch_vccz .LBB0_968
	s_barrier

.LBB0_1082:
	s_add_u32 s23, s30, s21
	s_addc_u32 s25, s31, 0
	s_add_u32 s37, s23, 0x100
	s_addc_u32 s44, s25, 0
	s_and_b64 s[42:43], s[40:41], exec
	s_cselect_b32 s45, s29, s44
	s_cselect_b32 s44, s28, s37
	s_add_u32 s21, s26, s21
	s_addc_u32 s37, s27, 0
	s_add_u32 s21, s21, 0x100
	s_addc_u32 s37, s37, 0
	s_and_b64 s[40:41], s[40:41], exec
	s_cselect_b32 s47, s35, s37
	s_cselect_b32 s46, s34, s21
	s_add_u32 s50, s23, 0x80080
	s_addc_u32 s51, s25, 0
	s_add_i32 s76, s62, s2
	ds_read_b128 v[146:149], v131
	ds_read_b128 v[150:153], v131 offset:1024
	ds_read_b128 v[154:157], v131 offset:2048
	ds_read_b128 v[158:161], v131 offset:3072
	ds_read_b128 v[166:169], v132
	ds_read_b128 v[170:173], v132 offset:1024
	ds_read_b128 v[174:177], v132 offset:2048
	ds_read_b128 v[180:183], v132 offset:3072
	s_add_i32 m0, s3, 0xc000
	s_add_i32 s77, s3, 0xe000
	s_add_i32 s73, s76, 0x2000
	s_add_u32 s48, s46, 0x80000
	s_addc_u32 s49, s47, 0
	s_add_i32 s75, s63, s2
	s_add_i32 s74, s75, 0x2000
	s_add_i32 s72, 0, 0x18000
	s_add_i32 s71, 0, 0x1c000
	s_add_u32 s42, s44, 0x80000
	s_addc_u32 s43, s45, 0
	s_add_i32 s37, s72, s2
	s_add_i32 s23, s37, 0x2000
	s_add_u32 s40, s46, 0x80080
	s_addc_u32 s41, s47, 0
	s_add_i32 s25, s71, s2
	s_add_i32 s21, s25, 0x2000
	v_lshl_add_u64 v[134:135], s[50:51], 0, v[138:139]
	ds_read_b128 v[184:187], v133
	ds_read_b128 v[188:191], v133 offset:1024
	ds_read_b128 v[192:195], v133 offset:2048
	ds_read_b128 v[196:199], v133 offset:3072
	ds_read_b128 v[200:203], v133 offset:4096
	ds_read_b128 v[204:207], v133 offset:5120
	ds_read_b128 v[210:213], v133 offset:6144
	ds_read_b128 v[214:217], v133 offset:7168
	global_load_lds_dwordx4 v[134:135], off
	v_lshl_add_u64 v[134:135], s[50:51], 0, v[142:143]
	s_mov_b32 m0, s77
	s_nop 0
	global_load_lds_dwordx4 v[134:135], off
	s_waitcnt vmcnt(8)
	s_waitcnt lgkmcnt(0)
	s_barrier
	s_setprio 1
	s_waitcnt lgkmcnt(0)
	v_mfma_f32_16x16x32_bf16 v[124:127], v[146:149], v[184:187], v[124:127]
	v_mfma_f32_16x16x32_bf16 v[120:123], v[154:157], v[184:187], v[120:123]
	v_mfma_f32_16x16x32_bf16 v[116:119], v[146:149], v[192:195], v[116:119]
	v_mfma_f32_16x16x32_bf16 v[112:115], v[154:157], v[192:195], v[112:115]
	v_mfma_f32_16x16x32_bf16 v[108:111], v[146:149], v[200:203], v[108:111]
	v_mfma_f32_16x16x32_bf16 v[104:107], v[154:157], v[200:203], v[104:107]
	v_mfma_f32_16x16x32_bf16 v[100:103], v[146:149], v[210:213], v[100:103]
	v_mfma_f32_16x16x32_bf16 v[96:99], v[154:157], v[210:213], v[96:99]
	v_mfma_f32_16x16x32_bf16 v[124:127], v[150:153], v[188:191], v[124:127]
	v_mfma_f32_16x16x32_bf16 v[120:123], v[158:161], v[188:191], v[120:123]
	v_mfma_f32_16x16x32_bf16 v[116:119], v[150:153], v[196:199], v[116:119]
	v_mfma_f32_16x16x32_bf16 v[112:115], v[158:161], v[196:199], v[112:115]
	v_mfma_f32_16x16x32_bf16 v[108:111], v[150:153], v[204:207], v[108:111]
	v_mfma_f32_16x16x32_bf16 v[104:107], v[158:161], v[204:207], v[104:107]
	v_mfma_f32_16x16x32_bf16 v[100:103], v[150:153], v[214:217], v[100:103]
	v_mfma_f32_16x16x32_bf16 v[96:99], v[158:161], v[214:217], v[96:99]
	v_mfma_f32_16x16x32_bf16 v[92:95], v[166:169], v[184:187], v[92:95]
	v_mfma_f32_16x16x32_bf16 v[88:91], v[174:177], v[184:187], v[88:91]
	v_mfma_f32_16x16x32_bf16 v[84:87], v[166:169], v[192:195], v[84:87]
	v_mfma_f32_16x16x32_bf16 v[80:83], v[174:177], v[192:195], v[80:83]
	v_mfma_f32_16x16x32_bf16 v[76:79], v[166:169], v[200:203], v[76:79]
	v_mfma_f32_16x16x32_bf16 v[72:75], v[174:177], v[200:203], v[72:75]
	v_mfma_f32_16x16x32_bf16 v[68:71], v[166:169], v[210:213], v[68:71]
	v_mfma_f32_16x16x32_bf16 v[64:67], v[174:177], v[210:213], v[64:67]
	v_mfma_f32_16x16x32_bf16 v[92:95], v[170:173], v[188:191], v[92:95]
	v_mfma_f32_16x16x32_bf16 v[88:91], v[180:183], v[188:191], v[88:91]
	v_mfma_f32_16x16x32_bf16 v[84:87], v[170:173], v[196:199], v[84:87]
	v_mfma_f32_16x16x32_bf16 v[80:83], v[180:183], v[196:199], v[80:83]
	v_mfma_f32_16x16x32_bf16 v[76:79], v[170:173], v[204:207], v[76:79]
	v_mfma_f32_16x16x32_bf16 v[72:75], v[180:183], v[204:207], v[72:75]
	v_mfma_f32_16x16x32_bf16 v[68:71], v[170:173], v[214:217], v[68:71]
	v_mfma_f32_16x16x32_bf16 v[64:67], v[180:183], v[214:217], v[64:67]
	s_setprio 0
	s_barrier
	s_mov_b32 m0, s76
	v_lshl_add_u64 v[134:135], s[46:47], 0, v[140:141]
	ds_read_b128 v[184:187], v133 offset:16384
	ds_read_b128 v[188:191], v133 offset:17408
	ds_read_b128 v[192:195], v133 offset:18432
	ds_read_b128 v[196:199], v133 offset:19456
	ds_read_b128 v[200:203], v133 offset:20480
	ds_read_b128 v[204:207], v133 offset:21504
	ds_read_b128 v[210:213], v133 offset:22528
	ds_read_b128 v[214:217], v133 offset:23552
	global_load_lds_dwordx4 v[134:135], off
	v_lshl_add_u64 v[162:163], s[46:47], 0, v[144:145]
	s_mov_b32 m0, s73
	v_lshl_add_u64 v[218:219], s[48:49], 0, v[140:141]
	global_load_lds_dwordx4 v[162:163], off
	s_mov_b32 m0, s75
	v_lshl_add_u64 v[220:221], s[44:45], 0, v[142:143]
	global_load_lds_dwordx4 v[218:219], off
	v_lshl_add_u64 v[218:219], s[48:49], 0, v[144:145]
	s_mov_b32 m0, s74
	s_nop 0
	global_load_lds_dwordx4 v[218:219], off
	v_lshl_add_u64 v[218:219], s[44:45], 0, v[138:139]
	s_mov_b32 m0, s3
	s_nop 0
	global_load_lds_dwordx4 v[218:219], off
	s_mov_b32 m0, s56
	s_nop 0
	global_load_lds_dwordx4 v[220:221], off
	s_waitcnt vmcnt(8)
	s_waitcnt lgkmcnt(0)
	s_barrier
	s_setprio 1
	s_waitcnt lgkmcnt(0)
	v_mfma_f32_16x16x32_bf16 v[60:63], v[146:149], v[184:187], v[60:63]
	v_mfma_f32_16x16x32_bf16 v[56:59], v[154:157], v[184:187], v[56:59]
	v_mfma_f32_16x16x32_bf16 v[52:55], v[146:149], v[192:195], v[52:55]
	v_mfma_f32_16x16x32_bf16 v[48:51], v[154:157], v[192:195], v[48:51]
	v_mfma_f32_16x16x32_bf16 v[44:47], v[146:149], v[200:203], v[44:47]
	v_mfma_f32_16x16x32_bf16 v[40:43], v[154:157], v[200:203], v[40:43]
	v_mfma_f32_16x16x32_bf16 v[36:39], v[146:149], v[210:213], v[36:39]
	v_mfma_f32_16x16x32_bf16 v[32:35], v[154:157], v[210:213], v[32:35]
	v_mfma_f32_16x16x32_bf16 v[60:63], v[150:153], v[188:191], v[60:63]
	v_mfma_f32_16x16x32_bf16 v[56:59], v[158:161], v[188:191], v[56:59]
	v_mfma_f32_16x16x32_bf16 v[52:55], v[150:153], v[196:199], v[52:55]
	v_mfma_f32_16x16x32_bf16 v[48:51], v[158:161], v[196:199], v[48:51]
	v_mfma_f32_16x16x32_bf16 v[44:47], v[150:153], v[204:207], v[44:47]
	v_mfma_f32_16x16x32_bf16 v[40:43], v[158:161], v[204:207], v[40:43]
	v_mfma_f32_16x16x32_bf16 v[36:39], v[150:153], v[214:217], v[36:39]
	v_mfma_f32_16x16x32_bf16 v[32:35], v[158:161], v[214:217], v[32:35]
	v_mfma_f32_16x16x32_bf16 v[28:31], v[166:169], v[184:187], v[28:31]
	v_mfma_f32_16x16x32_bf16 v[24:27], v[174:177], v[184:187], v[24:27]
	v_mfma_f32_16x16x32_bf16 v[20:23], v[166:169], v[192:195], v[20:23]
	v_mfma_f32_16x16x32_bf16 v[16:19], v[174:177], v[192:195], v[16:19]
	v_mfma_f32_16x16x32_bf16 v[12:15], v[166:169], v[200:203], v[12:15]
	v_mfma_f32_16x16x32_bf16 v[8:11], v[174:177], v[200:203], v[8:11]
	v_mfma_f32_16x16x32_bf16 v[4:7], v[166:169], v[210:213], v[4:7]
	v_mfma_f32_16x16x32_bf16 v[0:3], v[174:177], v[210:213], v[0:3]
	v_mfma_f32_16x16x32_bf16 v[28:31], v[170:173], v[188:191], v[28:31]
	v_mfma_f32_16x16x32_bf16 v[24:27], v[180:183], v[188:191], v[24:27]
	v_mfma_f32_16x16x32_bf16 v[20:23], v[170:173], v[196:199], v[20:23]
	v_mfma_f32_16x16x32_bf16 v[16:19], v[180:183], v[196:199], v[16:19]
	v_mfma_f32_16x16x32_bf16 v[12:15], v[170:173], v[204:207], v[12:15]
	v_mfma_f32_16x16x32_bf16 v[8:11], v[180:183], v[204:207], v[8:11]
	v_mfma_f32_16x16x32_bf16 v[4:7], v[170:173], v[214:217], v[4:7]
	v_mfma_f32_16x16x32_bf16 v[0:3], v[180:183], v[214:217], v[0:3]
	s_setprio 0
	s_barrier
	v_add_u32_e32 v137, s72, v130
	ds_read_b128 v[146:149], v137
	ds_read_b128 v[150:153], v137 offset:1024
	ds_read_b128 v[154:157], v137 offset:2048
	ds_read_b128 v[158:161], v137 offset:3072
	v_add_u32_e32 v137, s71, v130
	ds_read_b128 v[166:169], v137
	ds_read_b128 v[170:173], v137 offset:1024
	ds_read_b128 v[174:177], v137 offset:2048
	ds_read_b128 v[180:183], v137 offset:3072
	s_mov_b32 m0, s57
	v_lshl_add_u64 v[222:223], s[42:43], 0, v[138:139]
	ds_read_b128 v[184:187], v133 offset:32768
	ds_read_b128 v[188:191], v133 offset:33792
	ds_read_b128 v[192:195], v133 offset:34816
	ds_read_b128 v[196:199], v133 offset:35840
	ds_read_b128 v[200:203], v133 offset:36864
	ds_read_b128 v[204:207], v133 offset:37888
	ds_read_b128 v[210:213], v133 offset:38912
	ds_read_b128 v[214:217], v133 offset:39936
	global_load_lds_dwordx4 v[222:223], off
	v_lshl_add_u64 v[222:223], s[42:43], 0, v[142:143]
	s_mov_b32 m0, s58
	s_nop 0
	global_load_lds_dwordx4 v[222:223], off
	s_waitcnt vmcnt(8)
	s_waitcnt lgkmcnt(0)
	s_barrier
	s_setprio 1
	s_waitcnt lgkmcnt(0)
	v_mfma_f32_16x16x32_bf16 v[124:127], v[146:149], v[184:187], v[124:127]
	v_mfma_f32_16x16x32_bf16 v[120:123], v[154:157], v[184:187], v[120:123]
	v_mfma_f32_16x16x32_bf16 v[116:119], v[146:149], v[192:195], v[116:119]
	v_mfma_f32_16x16x32_bf16 v[112:115], v[154:157], v[192:195], v[112:115]
	v_mfma_f32_16x16x32_bf16 v[108:111], v[146:149], v[200:203], v[108:111]
	v_mfma_f32_16x16x32_bf16 v[104:107], v[154:157], v[200:203], v[104:107]
	v_mfma_f32_16x16x32_bf16 v[100:103], v[146:149], v[210:213], v[100:103]
	v_mfma_f32_16x16x32_bf16 v[96:99], v[154:157], v[210:213], v[96:99]
	v_mfma_f32_16x16x32_bf16 v[124:127], v[150:153], v[188:191], v[124:127]
	v_mfma_f32_16x16x32_bf16 v[120:123], v[158:161], v[188:191], v[120:123]
	v_mfma_f32_16x16x32_bf16 v[116:119], v[150:153], v[196:199], v[116:119]
	v_mfma_f32_16x16x32_bf16 v[112:115], v[158:161], v[196:199], v[112:115]
	v_mfma_f32_16x16x32_bf16 v[108:111], v[150:153], v[204:207], v[108:111]
	v_mfma_f32_16x16x32_bf16 v[104:107], v[158:161], v[204:207], v[104:107]
	v_mfma_f32_16x16x32_bf16 v[100:103], v[150:153], v[214:217], v[100:103]
	v_mfma_f32_16x16x32_bf16 v[96:99], v[158:161], v[214:217], v[96:99]
	v_mfma_f32_16x16x32_bf16 v[92:95], v[166:169], v[184:187], v[92:95]
	v_mfma_f32_16x16x32_bf16 v[88:91], v[174:177], v[184:187], v[88:91]
	v_mfma_f32_16x16x32_bf16 v[84:87], v[166:169], v[192:195], v[84:87]
	v_mfma_f32_16x16x32_bf16 v[80:83], v[174:177], v[192:195], v[80:83]
	v_mfma_f32_16x16x32_bf16 v[76:79], v[166:169], v[200:203], v[76:79]
	v_mfma_f32_16x16x32_bf16 v[72:75], v[174:177], v[200:203], v[72:75]
	v_mfma_f32_16x16x32_bf16 v[68:71], v[166:169], v[210:213], v[68:71]
	v_mfma_f32_16x16x32_bf16 v[64:67], v[174:177], v[210:213], v[64:67]
	v_mfma_f32_16x16x32_bf16 v[92:95], v[170:173], v[188:191], v[92:95]
	v_mfma_f32_16x16x32_bf16 v[88:91], v[180:183], v[188:191], v[88:91]
	v_mfma_f32_16x16x32_bf16 v[84:87], v[170:173], v[196:199], v[84:87]
	v_mfma_f32_16x16x32_bf16 v[80:83], v[180:183], v[196:199], v[80:83]
	v_mfma_f32_16x16x32_bf16 v[76:79], v[170:173], v[204:207], v[76:79]
	v_mfma_f32_16x16x32_bf16 v[72:75], v[180:183], v[204:207], v[72:75]
	v_mfma_f32_16x16x32_bf16 v[68:71], v[170:173], v[214:217], v[68:71]
	v_mfma_f32_16x16x32_bf16 v[64:67], v[180:183], v[214:217], v[64:67]
	s_setprio 0
	s_barrier
	s_mov_b32 m0, s37
	v_lshl_add_u64 v[134:135], v[134:135], 0, s[16:17]
	ds_read_b128 v[184:187], v133 offset:49152
	ds_read_b128 v[188:191], v133 offset:50176
	ds_read_b128 v[192:195], v133 offset:51200
	ds_read_b128 v[196:199], v133 offset:52224
	ds_read_b128 v[200:203], v133 offset:53248
	ds_read_b128 v[204:207], v133 offset:54272
	ds_read_b128 v[210:213], v133 offset:55296
	ds_read_b128 v[214:217], v133 offset:56320
	global_load_lds_dwordx4 v[134:135], off
	v_lshl_add_u64 v[134:135], v[162:163], 0, s[16:17]
	s_mov_b32 m0, s23
	s_nop 0
	global_load_lds_dwordx4 v[134:135], off
	v_lshl_add_u64 v[134:135], s[40:41], 0, v[140:141]
	s_mov_b32 m0, s25
	s_nop 0
	global_load_lds_dwordx4 v[134:135], off
	v_lshl_add_u64 v[134:135], s[40:41], 0, v[144:145]
	s_mov_b32 m0, s21
	s_nop 0
	global_load_lds_dwordx4 v[134:135], off
	v_lshl_add_u64 v[134:135], v[218:219], 0, s[16:17]
	s_mov_b32 m0, s60
	s_nop 0
	global_load_lds_dwordx4 v[134:135], off
	v_lshl_add_u64 v[134:135], v[220:221], 0, s[16:17]
	s_mov_b32 m0, s61
	s_nop 0
	global_load_lds_dwordx4 v[134:135], off
	s_waitcnt vmcnt(8)
	s_waitcnt lgkmcnt(0)
	s_barrier
	s_setprio 1
	s_waitcnt lgkmcnt(0)
	v_mfma_f32_16x16x32_bf16 v[60:63], v[146:149], v[184:187], v[60:63]
	v_mfma_f32_16x16x32_bf16 v[56:59], v[154:157], v[184:187], v[56:59]
	v_mfma_f32_16x16x32_bf16 v[52:55], v[146:149], v[192:195], v[52:55]
	v_mfma_f32_16x16x32_bf16 v[48:51], v[154:157], v[192:195], v[48:51]
	v_mfma_f32_16x16x32_bf16 v[44:47], v[146:149], v[200:203], v[44:47]
	v_mfma_f32_16x16x32_bf16 v[40:43], v[154:157], v[200:203], v[40:43]
	v_mfma_f32_16x16x32_bf16 v[36:39], v[146:149], v[210:213], v[36:39]
	v_mfma_f32_16x16x32_bf16 v[32:35], v[154:157], v[210:213], v[32:35]
	v_mfma_f32_16x16x32_bf16 v[60:63], v[150:153], v[188:191], v[60:63]
	v_mfma_f32_16x16x32_bf16 v[56:59], v[158:161], v[188:191], v[56:59]
	v_mfma_f32_16x16x32_bf16 v[52:55], v[150:153], v[196:199], v[52:55]
	v_mfma_f32_16x16x32_bf16 v[48:51], v[158:161], v[196:199], v[48:51]
	v_mfma_f32_16x16x32_bf16 v[44:47], v[150:153], v[204:207], v[44:47]
	v_mfma_f32_16x16x32_bf16 v[40:43], v[158:161], v[204:207], v[40:43]
	v_mfma_f32_16x16x32_bf16 v[36:39], v[150:153], v[214:217], v[36:39]
	v_mfma_f32_16x16x32_bf16 v[32:35], v[158:161], v[214:217], v[32:35]
	v_mfma_f32_16x16x32_bf16 v[28:31], v[166:169], v[184:187], v[28:31]
	v_mfma_f32_16x16x32_bf16 v[24:27], v[174:177], v[184:187], v[24:27]
	v_mfma_f32_16x16x32_bf16 v[20:23], v[166:169], v[192:195], v[20:23]
	v_mfma_f32_16x16x32_bf16 v[16:19], v[174:177], v[192:195], v[16:19]
	v_mfma_f32_16x16x32_bf16 v[12:15], v[166:169], v[200:203], v[12:15]
	v_mfma_f32_16x16x32_bf16 v[8:11], v[174:177], v[200:203], v[8:11]
	v_mfma_f32_16x16x32_bf16 v[4:7], v[166:169], v[210:213], v[4:7]
	v_mfma_f32_16x16x32_bf16 v[0:3], v[174:177], v[210:213], v[0:3]
	v_mfma_f32_16x16x32_bf16 v[28:31], v[170:173], v[188:191], v[28:31]
	v_mfma_f32_16x16x32_bf16 v[24:27], v[180:183], v[188:191], v[24:27]
	v_mfma_f32_16x16x32_bf16 v[20:23], v[170:173], v[196:199], v[20:23]
	v_mfma_f32_16x16x32_bf16 v[16:19], v[180:183], v[196:199], v[16:19]
	v_mfma_f32_16x16x32_bf16 v[12:15], v[170:173], v[204:207], v[12:15]
	v_mfma_f32_16x16x32_bf16 v[8:11], v[180:183], v[204:207], v[8:11]
	v_mfma_f32_16x16x32_bf16 v[4:7], v[170:173], v[214:217], v[4:7]
	v_mfma_f32_16x16x32_bf16 v[0:3], v[180:183], v[214:217], v[0:3]
	s_setprio 0
	s_barrier
	s_movk_i32 s21, 0x100
	s_andn2_b64 vcc, exec, s[38:39]
	s_mov_b64 s[40:41], -1
	s_mov_b64 s[38:39], 0
	s_cbranch_vccz .LBB0_1082
	s_and_b64 vcc, exec, s[18:19]
	s_cbranch_vccz .LBB0_1085
	s_barrier

.LBB0_1298:
	ds_read_b128 v[162:165], v159
	ds_read_b128 v[166:169], v159 offset:1024
	ds_read_b128 v[170:173], v159 offset:2048
	ds_read_b128 v[174:177], v159 offset:3072
	ds_read_b128 v[180:183], v160
	ds_read_b128 v[184:187], v160 offset:1024
	ds_read_b128 v[188:191], v160 offset:2048
	ds_read_b128 v[192:195], v160 offset:3072
	s_add_u32 s28, s26, 0xfff80080
	s_addc_u32 s29, s27, -1
	s_cmp_eq_u32 s49, 28
	s_cselect_b32 s31, s3, s29
	s_cselect_b32 s30, s19, s28
	s_cselect_b32 s29, s17, s48
	s_cselect_b32 s28, s46, s47
	v_lshl_add_u64 v[230:231], s[26:27], 0, v[138:139]
	s_add_i32 m0, s25, 0xc000
	ds_read_b128 v[196:199], v161
	ds_read_b128 v[200:203], v161 offset:1024
	ds_read_b128 v[204:207], v161 offset:2048
	ds_read_b128 v[210:213], v161 offset:3072
	ds_read_b128 v[214:217], v161 offset:4096
	ds_read_b128 v[218:221], v161 offset:5120
	ds_read_b128 v[222:225], v161 offset:6144
	ds_read_b128 v[226:229], v161 offset:7168
	global_load_lds_dwordx4 v[230:231], off
	v_lshl_add_u64 v[230:231], s[26:27], 0, v[140:141]
	s_add_i32 m0, s25, 0xe000
	s_nop 0
	global_load_lds_dwordx4 v[230:231], off
	s_waitcnt vmcnt(8)
	s_waitcnt lgkmcnt(0)
	s_barrier
	s_setprio 1
	s_waitcnt lgkmcnt(0)
	v_mfma_f32_16x16x32_bf16 v[124:127], v[162:165], v[196:199], v[124:127]
	v_mfma_f32_16x16x32_bf16 v[116:119], v[170:173], v[196:199], v[116:119]
	v_mfma_f32_16x16x32_bf16 v[108:111], v[162:165], v[204:207], v[108:111]
	v_mfma_f32_16x16x32_bf16 v[100:103], v[170:173], v[204:207], v[100:103]
	v_mfma_f32_16x16x32_bf16 v[92:95], v[162:165], v[214:217], v[92:95]
	v_mfma_f32_16x16x32_bf16 v[84:87], v[170:173], v[214:217], v[84:87]
	v_mfma_f32_16x16x32_bf16 v[76:79], v[162:165], v[222:225], v[76:79]
	v_mfma_f32_16x16x32_bf16 v[68:71], v[170:173], v[222:225], v[68:71]
	v_mfma_f32_16x16x32_bf16 v[124:127], v[166:169], v[200:203], v[124:127]
	v_mfma_f32_16x16x32_bf16 v[116:119], v[174:177], v[200:203], v[116:119]
	v_mfma_f32_16x16x32_bf16 v[108:111], v[166:169], v[210:213], v[108:111]
	v_mfma_f32_16x16x32_bf16 v[100:103], v[174:177], v[210:213], v[100:103]
	v_mfma_f32_16x16x32_bf16 v[92:95], v[166:169], v[218:221], v[92:95]
	v_mfma_f32_16x16x32_bf16 v[84:87], v[174:177], v[218:221], v[84:87]
	v_mfma_f32_16x16x32_bf16 v[76:79], v[166:169], v[226:229], v[76:79]
	v_mfma_f32_16x16x32_bf16 v[68:71], v[174:177], v[226:229], v[68:71]
	v_mfma_f32_16x16x32_bf16 v[120:123], v[180:183], v[196:199], v[120:123]
	v_mfma_f32_16x16x32_bf16 v[112:115], v[188:191], v[196:199], v[112:115]
	v_mfma_f32_16x16x32_bf16 v[104:107], v[180:183], v[204:207], v[104:107]
	v_mfma_f32_16x16x32_bf16 v[96:99], v[188:191], v[204:207], v[96:99]
	v_mfma_f32_16x16x32_bf16 v[88:91], v[180:183], v[214:217], v[88:91]
	v_mfma_f32_16x16x32_bf16 v[80:83], v[188:191], v[214:217], v[80:83]
	v_mfma_f32_16x16x32_bf16 v[72:75], v[180:183], v[222:225], v[72:75]
	v_mfma_f32_16x16x32_bf16 v[64:67], v[188:191], v[222:225], v[64:67]
	v_mfma_f32_16x16x32_bf16 v[120:123], v[184:187], v[200:203], v[120:123]
	v_mfma_f32_16x16x32_bf16 v[112:115], v[192:195], v[200:203], v[112:115]
	v_mfma_f32_16x16x32_bf16 v[104:107], v[184:187], v[210:213], v[104:107]
	v_mfma_f32_16x16x32_bf16 v[96:99], v[192:195], v[210:213], v[96:99]
	v_mfma_f32_16x16x32_bf16 v[88:91], v[184:187], v[218:221], v[88:91]
	v_mfma_f32_16x16x32_bf16 v[80:83], v[192:195], v[218:221], v[80:83]
	v_mfma_f32_16x16x32_bf16 v[72:75], v[184:187], v[226:229], v[72:75]
	v_mfma_f32_16x16x32_bf16 v[64:67], v[192:195], v[226:229], v[64:67]
	s_setprio 0
	s_barrier
	s_add_i32 s50, s43, s36
	v_lshl_add_u64 v[230:231], s[28:29], 0, v[132:133]
	s_mov_b32 m0, s50
	ds_read_b128 v[196:199], v161 offset:16384
	ds_read_b128 v[200:203], v161 offset:17408
	ds_read_b128 v[204:207], v161 offset:18432
	ds_read_b128 v[210:213], v161 offset:19456
	ds_read_b128 v[214:217], v161 offset:20480
	ds_read_b128 v[218:221], v161 offset:21504
	ds_read_b128 v[222:225], v161 offset:22528
	ds_read_b128 v[226:229], v161 offset:23552
	global_load_lds_dwordx4 v[230:231], off
	s_add_i32 m0, s50, 0x2000
	s_add_u32 s50, s28, 0x80000
	v_lshl_add_u64 v[232:233], s[28:29], 0, v[136:137]
	s_addc_u32 s51, s29, 0
	s_add_i32 s56, s44, s36
	global_load_lds_dwordx4 v[232:233], off
	v_lshl_add_u64 v[234:235], s[50:51], 0, v[132:133]
	s_mov_b32 m0, s56
	v_lshl_add_u64 v[236:237], s[30:31], 0, v[134:135]
	global_load_lds_dwordx4 v[234:235], off
	v_lshl_add_u64 v[234:235], s[50:51], 0, v[136:137]
	s_add_i32 m0, s56, 0x2000
	s_nop 0
	global_load_lds_dwordx4 v[234:235], off
	v_lshl_add_u64 v[234:235], s[30:31], 0, v[130:131]
	s_mov_b32 m0, s25
	s_nop 0
	global_load_lds_dwordx4 v[234:235], off
	s_mov_b32 m0, s37
	s_nop 0
	global_load_lds_dwordx4 v[236:237], off
	s_waitcnt vmcnt(8)
	s_waitcnt lgkmcnt(0)
	s_barrier
	s_setprio 1
	s_waitcnt lgkmcnt(0)
	v_mfma_f32_16x16x32_bf16 v[60:63], v[162:165], v[196:199], v[60:63]
	v_mfma_f32_16x16x32_bf16 v[52:55], v[170:173], v[196:199], v[52:55]
	v_mfma_f32_16x16x32_bf16 v[44:47], v[162:165], v[204:207], v[44:47]
	v_mfma_f32_16x16x32_bf16 v[36:39], v[170:173], v[204:207], v[36:39]
	v_mfma_f32_16x16x32_bf16 v[28:31], v[162:165], v[214:217], v[28:31]
	v_mfma_f32_16x16x32_bf16 v[20:23], v[170:173], v[214:217], v[20:23]
	v_mfma_f32_16x16x32_bf16 v[12:15], v[162:165], v[222:225], v[12:15]
	v_mfma_f32_16x16x32_bf16 v[4:7], v[170:173], v[222:225], v[4:7]
	v_mfma_f32_16x16x32_bf16 v[60:63], v[166:169], v[200:203], v[60:63]
	v_mfma_f32_16x16x32_bf16 v[52:55], v[174:177], v[200:203], v[52:55]
	v_mfma_f32_16x16x32_bf16 v[44:47], v[166:169], v[210:213], v[44:47]
	v_mfma_f32_16x16x32_bf16 v[36:39], v[174:177], v[210:213], v[36:39]
	v_mfma_f32_16x16x32_bf16 v[28:31], v[166:169], v[218:221], v[28:31]
	v_mfma_f32_16x16x32_bf16 v[20:23], v[174:177], v[218:221], v[20:23]
	v_mfma_f32_16x16x32_bf16 v[12:15], v[166:169], v[226:229], v[12:15]
	v_mfma_f32_16x16x32_bf16 v[4:7], v[174:177], v[226:229], v[4:7]
	v_mfma_f32_16x16x32_bf16 v[56:59], v[180:183], v[196:199], v[56:59]
	v_mfma_f32_16x16x32_bf16 v[48:51], v[188:191], v[196:199], v[48:51]
	v_mfma_f32_16x16x32_bf16 v[40:43], v[180:183], v[204:207], v[40:43]
	v_mfma_f32_16x16x32_bf16 v[32:35], v[188:191], v[204:207], v[32:35]
	v_mfma_f32_16x16x32_bf16 v[24:27], v[180:183], v[214:217], v[24:27]
	v_mfma_f32_16x16x32_bf16 v[16:19], v[188:191], v[214:217], v[16:19]
	v_mfma_f32_16x16x32_bf16 v[8:11], v[180:183], v[222:225], v[8:11]
	v_mfma_f32_16x16x32_bf16 v[0:3], v[188:191], v[222:225], v[0:3]
	v_mfma_f32_16x16x32_bf16 v[56:59], v[184:187], v[200:203], v[56:59]
	v_mfma_f32_16x16x32_bf16 v[48:51], v[192:195], v[200:203], v[48:51]
	v_mfma_f32_16x16x32_bf16 v[40:43], v[184:187], v[210:213], v[40:43]
	v_mfma_f32_16x16x32_bf16 v[32:35], v[192:195], v[210:213], v[32:35]
	v_mfma_f32_16x16x32_bf16 v[24:27], v[184:187], v[218:221], v[24:27]
	v_mfma_f32_16x16x32_bf16 v[16:19], v[192:195], v[218:221], v[16:19]
	v_mfma_f32_16x16x32_bf16 v[8:11], v[184:187], v[226:229], v[8:11]
	v_mfma_f32_16x16x32_bf16 v[0:3], v[192:195], v[226:229], v[0:3]
	s_setprio 0
	s_barrier
	s_add_i32 s50, 0, 0x18000
	s_add_i32 s51, 0, 0x1c000
	v_add_u32_e32 v174, s50, v157
	v_add_u32_e32 v178, s51, v157
	ds_read_b128 v[162:165], v174
	ds_read_b128 v[166:169], v174 offset:1024
	ds_read_b128 v[170:173], v174 offset:2048
	ds_read_b128 v[174:177], v174 offset:3072
	ds_read_b128 v[180:183], v178
	ds_read_b128 v[184:187], v178 offset:1024
	ds_read_b128 v[188:191], v178 offset:2048
	ds_read_b128 v[192:195], v178 offset:3072
	s_add_u32 s30, s30, 0x80000
	s_addc_u32 s31, s31, 0
	s_mov_b32 m0, s38
	v_lshl_add_u64 v[238:239], s[30:31], 0, v[130:131]
	ds_read_b128 v[196:199], v161 offset:32768
	ds_read_b128 v[200:203], v161 offset:33792
	ds_read_b128 v[204:207], v161 offset:34816
	ds_read_b128 v[210:213], v161 offset:35840
	ds_read_b128 v[214:217], v161 offset:36864
	ds_read_b128 v[218:221], v161 offset:37888
	ds_read_b128 v[222:225], v161 offset:38912
	ds_read_b128 v[226:229], v161 offset:39936
	global_load_lds_dwordx4 v[238:239], off
	v_lshl_add_u64 v[238:239], s[30:31], 0, v[134:135]
	s_mov_b32 m0, s39
	s_nop 0
	global_load_lds_dwordx4 v[238:239], off
	s_waitcnt vmcnt(8)
	s_waitcnt lgkmcnt(0)
	s_barrier
	s_setprio 1
	s_waitcnt lgkmcnt(0)
	v_mfma_f32_16x16x32_bf16 v[124:127], v[162:165], v[196:199], v[124:127]
	v_mfma_f32_16x16x32_bf16 v[116:119], v[170:173], v[196:199], v[116:119]
	v_mfma_f32_16x16x32_bf16 v[108:111], v[162:165], v[204:207], v[108:111]
	v_mfma_f32_16x16x32_bf16 v[100:103], v[170:173], v[204:207], v[100:103]
	v_mfma_f32_16x16x32_bf16 v[92:95], v[162:165], v[214:217], v[92:95]
	v_mfma_f32_16x16x32_bf16 v[84:87], v[170:173], v[214:217], v[84:87]
	v_mfma_f32_16x16x32_bf16 v[76:79], v[162:165], v[222:225], v[76:79]
	v_mfma_f32_16x16x32_bf16 v[68:71], v[170:173], v[222:225], v[68:71]
	v_mfma_f32_16x16x32_bf16 v[124:127], v[166:169], v[200:203], v[124:127]
	v_mfma_f32_16x16x32_bf16 v[116:119], v[174:177], v[200:203], v[116:119]
	v_mfma_f32_16x16x32_bf16 v[108:111], v[166:169], v[210:213], v[108:111]
	v_mfma_f32_16x16x32_bf16 v[100:103], v[174:177], v[210:213], v[100:103]
	v_mfma_f32_16x16x32_bf16 v[92:95], v[166:169], v[218:221], v[92:95]
	v_mfma_f32_16x16x32_bf16 v[84:87], v[174:177], v[218:221], v[84:87]
	v_mfma_f32_16x16x32_bf16 v[76:79], v[166:169], v[226:229], v[76:79]
	v_mfma_f32_16x16x32_bf16 v[68:71], v[174:177], v[226:229], v[68:71]
	v_mfma_f32_16x16x32_bf16 v[120:123], v[180:183], v[196:199], v[120:123]
	v_mfma_f32_16x16x32_bf16 v[112:115], v[188:191], v[196:199], v[112:115]
	v_mfma_f32_16x16x32_bf16 v[104:107], v[180:183], v[204:207], v[104:107]
	v_mfma_f32_16x16x32_bf16 v[96:99], v[188:191], v[204:207], v[96:99]
	v_mfma_f32_16x16x32_bf16 v[88:91], v[180:183], v[214:217], v[88:91]
	v_mfma_f32_16x16x32_bf16 v[80:83], v[188:191], v[214:217], v[80:83]
	v_mfma_f32_16x16x32_bf16 v[72:75], v[180:183], v[222:225], v[72:75]
	v_mfma_f32_16x16x32_bf16 v[64:67], v[188:191], v[222:225], v[64:67]
	v_mfma_f32_16x16x32_bf16 v[120:123], v[184:187], v[200:203], v[120:123]
	v_mfma_f32_16x16x32_bf16 v[112:115], v[192:195], v[200:203], v[112:115]
	v_mfma_f32_16x16x32_bf16 v[104:107], v[184:187], v[210:213], v[104:107]
	v_mfma_f32_16x16x32_bf16 v[96:99], v[192:195], v[210:213], v[96:99]
	v_mfma_f32_16x16x32_bf16 v[88:91], v[184:187], v[218:221], v[88:91]
	v_mfma_f32_16x16x32_bf16 v[80:83], v[192:195], v[218:221], v[80:83]
	v_mfma_f32_16x16x32_bf16 v[72:75], v[184:187], v[226:229], v[72:75]
	v_mfma_f32_16x16x32_bf16 v[64:67], v[192:195], v[226:229], v[64:67]
	s_setprio 0
	s_barrier
	s_add_i32 s30, s50, s36
	v_lshl_add_u64 v[230:231], v[230:231], 0, s[12:13]
	s_mov_b32 m0, s30
	ds_read_b128 v[196:199], v161 offset:49152
	ds_read_b128 v[200:203], v161 offset:50176
	ds_read_b128 v[204:207], v161 offset:51200
	ds_read_b128 v[210:213], v161 offset:52224
	ds_read_b128 v[214:217], v161 offset:53248
	ds_read_b128 v[218:221], v161 offset:54272
	ds_read_b128 v[222:225], v161 offset:55296
	ds_read_b128 v[226:229], v161 offset:56320
	global_load_lds_dwordx4 v[230:231], off
	s_add_i32 m0, s30, 0x2000
	s_add_u32 s28, s28, 0x80080
	v_lshl_add_u64 v[230:231], v[232:233], 0, s[12:13]
	s_addc_u32 s29, s29, 0
	s_add_i32 s30, s51, s36
	global_load_lds_dwordx4 v[230:231], off
	v_lshl_add_u64 v[230:231], s[28:29], 0, v[132:133]
	s_mov_b32 m0, s30
	s_nop 0
	global_load_lds_dwordx4 v[230:231], off
	v_lshl_add_u64 v[230:231], s[28:29], 0, v[136:137]
	s_add_i32 m0, s30, 0x2000
	s_nop 0
	global_load_lds_dwordx4 v[230:231], off
	v_lshl_add_u64 v[230:231], v[234:235], 0, s[12:13]
	s_mov_b32 m0, s40
	s_nop 0
	global_load_lds_dwordx4 v[230:231], off
	v_lshl_add_u64 v[230:231], v[236:237], 0, s[12:13]
	s_mov_b32 m0, s41
	s_nop 0
	global_load_lds_dwordx4 v[230:231], off
	s_waitcnt vmcnt(8)
	s_waitcnt lgkmcnt(0)
	s_barrier
	s_setprio 1
	s_waitcnt lgkmcnt(0)
	v_mfma_f32_16x16x32_bf16 v[60:63], v[162:165], v[196:199], v[60:63]
	v_mfma_f32_16x16x32_bf16 v[52:55], v[170:173], v[196:199], v[52:55]
	v_mfma_f32_16x16x32_bf16 v[44:47], v[162:165], v[204:207], v[44:47]
	v_mfma_f32_16x16x32_bf16 v[36:39], v[170:173], v[204:207], v[36:39]
	v_mfma_f32_16x16x32_bf16 v[28:31], v[162:165], v[214:217], v[28:31]
	v_mfma_f32_16x16x32_bf16 v[20:23], v[170:173], v[214:217], v[20:23]
	v_mfma_f32_16x16x32_bf16 v[12:15], v[162:165], v[222:225], v[12:15]
	v_mfma_f32_16x16x32_bf16 v[4:7], v[170:173], v[222:225], v[4:7]
	v_mfma_f32_16x16x32_bf16 v[60:63], v[166:169], v[200:203], v[60:63]
	v_mfma_f32_16x16x32_bf16 v[52:55], v[174:177], v[200:203], v[52:55]
	v_mfma_f32_16x16x32_bf16 v[44:47], v[166:169], v[210:213], v[44:47]
	v_mfma_f32_16x16x32_bf16 v[36:39], v[174:177], v[210:213], v[36:39]
	v_mfma_f32_16x16x32_bf16 v[28:31], v[166:169], v[218:221], v[28:31]
	v_mfma_f32_16x16x32_bf16 v[20:23], v[174:177], v[218:221], v[20:23]
	v_mfma_f32_16x16x32_bf16 v[12:15], v[166:169], v[226:229], v[12:15]
	v_mfma_f32_16x16x32_bf16 v[4:7], v[174:177], v[226:229], v[4:7]
	v_mfma_f32_16x16x32_bf16 v[56:59], v[180:183], v[196:199], v[56:59]
	v_mfma_f32_16x16x32_bf16 v[48:51], v[188:191], v[196:199], v[48:51]
	v_mfma_f32_16x16x32_bf16 v[40:43], v[180:183], v[204:207], v[40:43]
	v_mfma_f32_16x16x32_bf16 v[32:35], v[188:191], v[204:207], v[32:35]
	v_mfma_f32_16x16x32_bf16 v[24:27], v[180:183], v[214:217], v[24:27]
	v_mfma_f32_16x16x32_bf16 v[16:19], v[188:191], v[214:217], v[16:19]
	v_mfma_f32_16x16x32_bf16 v[8:11], v[180:183], v[222:225], v[8:11]
	v_mfma_f32_16x16x32_bf16 v[0:3], v[188:191], v[222:225], v[0:3]
	v_mfma_f32_16x16x32_bf16 v[56:59], v[184:187], v[200:203], v[56:59]
	v_mfma_f32_16x16x32_bf16 v[48:51], v[192:195], v[200:203], v[48:51]
	v_mfma_f32_16x16x32_bf16 v[40:43], v[184:187], v[210:213], v[40:43]
	v_mfma_f32_16x16x32_bf16 v[32:35], v[192:195], v[210:213], v[32:35]
	v_mfma_f32_16x16x32_bf16 v[24:27], v[184:187], v[218:221], v[24:27]
	v_mfma_f32_16x16x32_bf16 v[16:19], v[192:195], v[218:221], v[16:19]
	v_mfma_f32_16x16x32_bf16 v[8:11], v[184:187], v[226:229], v[8:11]
	v_mfma_f32_16x16x32_bf16 v[0:3], v[192:195], v[226:229], v[0:3]
	s_setprio 0
	s_barrier
	s_add_i32 s49, s49, 2
	s_add_u32 s26, s26, 0x100
	s_addc_u32 s27, s27, 0
	s_add_u32 s47, s47, 0x100
	s_addc_u32 s48, s48, 0
	s_cmp_gt_u32 s49, 29
	s_cbranch_scc0 .LBB0_1298
	s_and_b64 vcc, exec, s[14:15]
	s_cbranch_vccz .LBB0_1301
	s_barrier

.LBB0_1327:
	s_add_u32 s25, s28, s23
	s_addc_u32 s27, s29, 0
	s_add_u32 s37, s25, 0x100
	s_addc_u32 s44, s27, 0
	s_and_b64 s[42:43], s[40:41], exec
	s_cselect_b32 s45, s31, s44
	s_cselect_b32 s44, s30, s37
	s_add_u32 s23, s20, s23
	s_addc_u32 s37, s21, 0
	s_add_u32 s23, s23, 0x100
	s_addc_u32 s37, s37, 0
	s_and_b64 s[40:41], s[40:41], exec
	s_cselect_b32 s47, s35, s37
	s_cselect_b32 s46, s34, s23
	s_add_u32 s50, s25, 0x80080
	s_addc_u32 s51, s27, 0
	s_add_i32 s84, s63, s2
	ds_read_b128 v[156:159], v129
	ds_read_b128 v[160:163], v129 offset:1024
	ds_read_b128 v[164:167], v129 offset:2048
	ds_read_b128 v[168:171], v129 offset:3072
	ds_read_b128 v[172:175], v141
	ds_read_b128 v[180:183], v141 offset:1024
	ds_read_b128 v[184:187], v141 offset:2048
	ds_read_b128 v[188:191], v141 offset:3072
	s_add_i32 m0, s3, 0xc000
	s_add_i32 s85, s3, 0xe000
	s_add_i32 s81, s84, 0x2000
	s_add_u32 s48, s46, 0x80000
	s_addc_u32 s49, s47, 0
	s_add_i32 s83, s64, s2
	s_add_i32 s82, s83, 0x2000
	s_add_i32 s80, 0, 0x18000
	s_add_i32 s79, 0, 0x1c000
	s_add_u32 s42, s44, 0x80000
	s_addc_u32 s43, s45, 0
	s_add_i32 s37, s80, s2
	s_add_i32 s25, s37, 0x2000
	s_add_u32 s40, s46, 0x80080
	s_addc_u32 s41, s47, 0
	s_add_i32 s27, s79, s2
	s_add_i32 s23, s27, 0x2000
	v_lshl_add_u64 v[176:177], s[50:51], 0, v[130:131]
	ds_read_b128 v[192:195], v142
	ds_read_b128 v[196:199], v142 offset:1024
	ds_read_b128 v[200:203], v142 offset:2048
	ds_read_b128 v[204:207], v142 offset:3072
	ds_read_b128 v[210:213], v142 offset:4096
	ds_read_b128 v[214:217], v142 offset:5120
	ds_read_b128 v[218:221], v142 offset:6144
	ds_read_b128 v[222:225], v142 offset:7168
	global_load_lds_dwordx4 v[176:177], off
	v_lshl_add_u64 v[176:177], s[50:51], 0, v[134:135]
	s_mov_b32 m0, s85
	s_nop 0
	global_load_lds_dwordx4 v[176:177], off
	s_waitcnt vmcnt(8)
	s_waitcnt lgkmcnt(0)
	s_barrier
	s_setprio 1
	s_waitcnt lgkmcnt(0)
	v_mfma_f32_16x16x32_bf16 v[124:127], v[156:159], v[192:195], v[124:127]
	v_mfma_f32_16x16x32_bf16 v[120:123], v[164:167], v[192:195], v[120:123]
	v_mfma_f32_16x16x32_bf16 v[116:119], v[156:159], v[200:203], v[116:119]
	v_mfma_f32_16x16x32_bf16 v[112:115], v[164:167], v[200:203], v[112:115]
	v_mfma_f32_16x16x32_bf16 v[108:111], v[156:159], v[210:213], v[108:111]
	v_mfma_f32_16x16x32_bf16 v[104:107], v[164:167], v[210:213], v[104:107]
	v_mfma_f32_16x16x32_bf16 v[100:103], v[156:159], v[218:221], v[100:103]
	v_mfma_f32_16x16x32_bf16 v[96:99], v[164:167], v[218:221], v[96:99]
	v_mfma_f32_16x16x32_bf16 v[124:127], v[160:163], v[196:199], v[124:127]
	v_mfma_f32_16x16x32_bf16 v[120:123], v[168:171], v[196:199], v[120:123]
	v_mfma_f32_16x16x32_bf16 v[116:119], v[160:163], v[204:207], v[116:119]
	v_mfma_f32_16x16x32_bf16 v[112:115], v[168:171], v[204:207], v[112:115]
	v_mfma_f32_16x16x32_bf16 v[108:111], v[160:163], v[214:217], v[108:111]
	v_mfma_f32_16x16x32_bf16 v[104:107], v[168:171], v[214:217], v[104:107]
	v_mfma_f32_16x16x32_bf16 v[100:103], v[160:163], v[222:225], v[100:103]
	v_mfma_f32_16x16x32_bf16 v[96:99], v[168:171], v[222:225], v[96:99]
	v_mfma_f32_16x16x32_bf16 v[92:95], v[172:175], v[192:195], v[92:95]
	v_mfma_f32_16x16x32_bf16 v[88:91], v[184:187], v[192:195], v[88:91]
	v_mfma_f32_16x16x32_bf16 v[84:87], v[172:175], v[200:203], v[84:87]
	v_mfma_f32_16x16x32_bf16 v[80:83], v[184:187], v[200:203], v[80:83]
	v_mfma_f32_16x16x32_bf16 v[76:79], v[172:175], v[210:213], v[76:79]
	v_mfma_f32_16x16x32_bf16 v[72:75], v[184:187], v[210:213], v[72:75]
	v_mfma_f32_16x16x32_bf16 v[68:71], v[172:175], v[218:221], v[68:71]
	v_mfma_f32_16x16x32_bf16 v[64:67], v[184:187], v[218:221], v[64:67]
	v_mfma_f32_16x16x32_bf16 v[92:95], v[180:183], v[196:199], v[92:95]
	v_mfma_f32_16x16x32_bf16 v[88:91], v[188:191], v[196:199], v[88:91]
	v_mfma_f32_16x16x32_bf16 v[84:87], v[180:183], v[204:207], v[84:87]
	v_mfma_f32_16x16x32_bf16 v[80:83], v[188:191], v[204:207], v[80:83]
	v_mfma_f32_16x16x32_bf16 v[76:79], v[180:183], v[214:217], v[76:79]
	v_mfma_f32_16x16x32_bf16 v[72:75], v[188:191], v[214:217], v[72:75]
	v_mfma_f32_16x16x32_bf16 v[68:71], v[180:183], v[222:225], v[68:71]
	v_mfma_f32_16x16x32_bf16 v[64:67], v[188:191], v[222:225], v[64:67]
	s_setprio 0
	s_barrier
	s_mov_b32 m0, s84
	v_lshl_add_u64 v[176:177], s[46:47], 0, v[132:133]
	ds_read_b128 v[192:195], v142 offset:16384
	ds_read_b128 v[196:199], v142 offset:17408
	ds_read_b128 v[200:203], v142 offset:18432
	ds_read_b128 v[204:207], v142 offset:19456
	ds_read_b128 v[210:213], v142 offset:20480
	ds_read_b128 v[214:217], v142 offset:21504
	ds_read_b128 v[218:221], v142 offset:22528
	ds_read_b128 v[222:225], v142 offset:23552
	global_load_lds_dwordx4 v[176:177], off
	v_lshl_add_u64 v[226:227], s[46:47], 0, v[136:137]
	s_mov_b32 m0, s81
	v_lshl_add_u64 v[228:229], s[48:49], 0, v[132:133]
	global_load_lds_dwordx4 v[226:227], off
	s_mov_b32 m0, s83
	v_lshl_add_u64 v[230:231], s[44:45], 0, v[134:135]
	global_load_lds_dwordx4 v[228:229], off
	v_lshl_add_u64 v[228:229], s[48:49], 0, v[136:137]
	s_mov_b32 m0, s82
	s_nop 0
	global_load_lds_dwordx4 v[228:229], off
	v_lshl_add_u64 v[228:229], s[44:45], 0, v[130:131]
	s_mov_b32 m0, s3
	s_nop 0
	global_load_lds_dwordx4 v[228:229], off
	s_mov_b32 m0, s56
	s_nop 0
	global_load_lds_dwordx4 v[230:231], off
	s_waitcnt vmcnt(8)
	s_waitcnt lgkmcnt(0)
	s_barrier
	s_setprio 1
	s_waitcnt lgkmcnt(0)
	v_mfma_f32_16x16x32_bf16 v[60:63], v[156:159], v[192:195], v[60:63]
	v_mfma_f32_16x16x32_bf16 v[56:59], v[164:167], v[192:195], v[56:59]
	v_mfma_f32_16x16x32_bf16 v[52:55], v[156:159], v[200:203], v[52:55]
	v_mfma_f32_16x16x32_bf16 v[48:51], v[164:167], v[200:203], v[48:51]
	v_mfma_f32_16x16x32_bf16 v[44:47], v[156:159], v[210:213], v[44:47]
	v_mfma_f32_16x16x32_bf16 v[40:43], v[164:167], v[210:213], v[40:43]
	v_mfma_f32_16x16x32_bf16 v[36:39], v[156:159], v[218:221], v[36:39]
	v_mfma_f32_16x16x32_bf16 v[32:35], v[164:167], v[218:221], v[32:35]
	v_mfma_f32_16x16x32_bf16 v[60:63], v[160:163], v[196:199], v[60:63]
	v_mfma_f32_16x16x32_bf16 v[56:59], v[168:171], v[196:199], v[56:59]
	v_mfma_f32_16x16x32_bf16 v[52:55], v[160:163], v[204:207], v[52:55]
	v_mfma_f32_16x16x32_bf16 v[48:51], v[168:171], v[204:207], v[48:51]
	v_mfma_f32_16x16x32_bf16 v[44:47], v[160:163], v[214:217], v[44:47]
	v_mfma_f32_16x16x32_bf16 v[40:43], v[168:171], v[214:217], v[40:43]
	v_mfma_f32_16x16x32_bf16 v[36:39], v[160:163], v[222:225], v[36:39]
	v_mfma_f32_16x16x32_bf16 v[32:35], v[168:171], v[222:225], v[32:35]
	v_mfma_f32_16x16x32_bf16 v[28:31], v[172:175], v[192:195], v[28:31]
	v_mfma_f32_16x16x32_bf16 v[24:27], v[184:187], v[192:195], v[24:27]
	v_mfma_f32_16x16x32_bf16 v[20:23], v[172:175], v[200:203], v[20:23]
	v_mfma_f32_16x16x32_bf16 v[16:19], v[184:187], v[200:203], v[16:19]
	v_mfma_f32_16x16x32_bf16 v[12:15], v[172:175], v[210:213], v[12:15]
	v_mfma_f32_16x16x32_bf16 v[8:11], v[184:187], v[210:213], v[8:11]
	v_mfma_f32_16x16x32_bf16 v[4:7], v[172:175], v[218:221], v[4:7]
	v_mfma_f32_16x16x32_bf16 v[0:3], v[184:187], v[218:221], v[0:3]
	v_mfma_f32_16x16x32_bf16 v[28:31], v[180:183], v[196:199], v[28:31]
	v_mfma_f32_16x16x32_bf16 v[24:27], v[188:191], v[196:199], v[24:27]
	v_mfma_f32_16x16x32_bf16 v[20:23], v[180:183], v[204:207], v[20:23]
	v_mfma_f32_16x16x32_bf16 v[16:19], v[188:191], v[204:207], v[16:19]
	v_mfma_f32_16x16x32_bf16 v[12:15], v[180:183], v[214:217], v[12:15]
	v_mfma_f32_16x16x32_bf16 v[8:11], v[188:191], v[214:217], v[8:11]
	v_mfma_f32_16x16x32_bf16 v[4:7], v[180:183], v[222:225], v[4:7]
	v_mfma_f32_16x16x32_bf16 v[0:3], v[188:191], v[222:225], v[0:3]
	s_setprio 0
	s_barrier
	v_add_u32_e32 v143, s80, v140
	ds_read_b128 v[156:159], v143
	ds_read_b128 v[160:163], v143 offset:1024
	ds_read_b128 v[164:167], v143 offset:2048
	ds_read_b128 v[168:171], v143 offset:3072
	v_add_u32_e32 v143, s79, v140
	ds_read_b128 v[172:175], v143
	ds_read_b128 v[180:183], v143 offset:1024
	ds_read_b128 v[184:187], v143 offset:2048
	ds_read_b128 v[188:191], v143 offset:3072
	s_mov_b32 m0, s57
	v_lshl_add_u64 v[232:233], s[42:43], 0, v[130:131]
	ds_read_b128 v[192:195], v142 offset:32768
	ds_read_b128 v[196:199], v142 offset:33792
	ds_read_b128 v[200:203], v142 offset:34816
	ds_read_b128 v[204:207], v142 offset:35840
	ds_read_b128 v[210:213], v142 offset:36864
	ds_read_b128 v[214:217], v142 offset:37888
	ds_read_b128 v[218:221], v142 offset:38912
	ds_read_b128 v[222:225], v142 offset:39936
	global_load_lds_dwordx4 v[232:233], off
	v_lshl_add_u64 v[232:233], s[42:43], 0, v[134:135]
	s_mov_b32 m0, s58
	s_nop 0
	global_load_lds_dwordx4 v[232:233], off
	s_waitcnt vmcnt(8)
	s_waitcnt lgkmcnt(0)
	s_barrier
	s_setprio 1
	s_waitcnt lgkmcnt(0)
	v_mfma_f32_16x16x32_bf16 v[124:127], v[156:159], v[192:195], v[124:127]
	v_mfma_f32_16x16x32_bf16 v[120:123], v[164:167], v[192:195], v[120:123]
	v_mfma_f32_16x16x32_bf16 v[116:119], v[156:159], v[200:203], v[116:119]
	v_mfma_f32_16x16x32_bf16 v[112:115], v[164:167], v[200:203], v[112:115]
	v_mfma_f32_16x16x32_bf16 v[108:111], v[156:159], v[210:213], v[108:111]
	v_mfma_f32_16x16x32_bf16 v[104:107], v[164:167], v[210:213], v[104:107]
	v_mfma_f32_16x16x32_bf16 v[100:103], v[156:159], v[218:221], v[100:103]
	v_mfma_f32_16x16x32_bf16 v[96:99], v[164:167], v[218:221], v[96:99]
	v_mfma_f32_16x16x32_bf16 v[124:127], v[160:163], v[196:199], v[124:127]
	v_mfma_f32_16x16x32_bf16 v[120:123], v[168:171], v[196:199], v[120:123]
	v_mfma_f32_16x16x32_bf16 v[116:119], v[160:163], v[204:207], v[116:119]
	v_mfma_f32_16x16x32_bf16 v[112:115], v[168:171], v[204:207], v[112:115]
	v_mfma_f32_16x16x32_bf16 v[108:111], v[160:163], v[214:217], v[108:111]
	v_mfma_f32_16x16x32_bf16 v[104:107], v[168:171], v[214:217], v[104:107]
	v_mfma_f32_16x16x32_bf16 v[100:103], v[160:163], v[222:225], v[100:103]
	v_mfma_f32_16x16x32_bf16 v[96:99], v[168:171], v[222:225], v[96:99]
	v_mfma_f32_16x16x32_bf16 v[92:95], v[172:175], v[192:195], v[92:95]
	v_mfma_f32_16x16x32_bf16 v[88:91], v[184:187], v[192:195], v[88:91]
	v_mfma_f32_16x16x32_bf16 v[84:87], v[172:175], v[200:203], v[84:87]
	v_mfma_f32_16x16x32_bf16 v[80:83], v[184:187], v[200:203], v[80:83]
	v_mfma_f32_16x16x32_bf16 v[76:79], v[172:175], v[210:213], v[76:79]
	v_mfma_f32_16x16x32_bf16 v[72:75], v[184:187], v[210:213], v[72:75]
	v_mfma_f32_16x16x32_bf16 v[68:71], v[172:175], v[218:221], v[68:71]
	v_mfma_f32_16x16x32_bf16 v[64:67], v[184:187], v[218:221], v[64:67]
	v_mfma_f32_16x16x32_bf16 v[92:95], v[180:183], v[196:199], v[92:95]
	v_mfma_f32_16x16x32_bf16 v[88:91], v[188:191], v[196:199], v[88:91]
	v_mfma_f32_16x16x32_bf16 v[84:87], v[180:183], v[204:207], v[84:87]
	v_mfma_f32_16x16x32_bf16 v[80:83], v[188:191], v[204:207], v[80:83]
	v_mfma_f32_16x16x32_bf16 v[76:79], v[180:183], v[214:217], v[76:79]
	v_mfma_f32_16x16x32_bf16 v[72:75], v[188:191], v[214:217], v[72:75]
	v_mfma_f32_16x16x32_bf16 v[68:71], v[180:183], v[222:225], v[68:71]
	v_mfma_f32_16x16x32_bf16 v[64:67], v[188:191], v[222:225], v[64:67]
	s_setprio 0
	s_barrier
	s_mov_b32 m0, s37
	v_lshl_add_u64 v[176:177], v[176:177], 0, s[16:17]
	ds_read_b128 v[192:195], v142 offset:49152
	ds_read_b128 v[196:199], v142 offset:50176
	ds_read_b128 v[200:203], v142 offset:51200
	ds_read_b128 v[204:207], v142 offset:52224
	ds_read_b128 v[210:213], v142 offset:53248
	ds_read_b128 v[214:217], v142 offset:54272
	ds_read_b128 v[218:221], v142 offset:55296
	ds_read_b128 v[222:225], v142 offset:56320
	global_load_lds_dwordx4 v[176:177], off
	v_lshl_add_u64 v[176:177], v[226:227], 0, s[16:17]
	s_mov_b32 m0, s25
	s_nop 0
	global_load_lds_dwordx4 v[176:177], off
	v_lshl_add_u64 v[176:177], s[40:41], 0, v[132:133]
	s_mov_b32 m0, s27
	s_nop 0
	global_load_lds_dwordx4 v[176:177], off
	v_lshl_add_u64 v[176:177], s[40:41], 0, v[136:137]
	s_mov_b32 m0, s23
	s_nop 0
	global_load_lds_dwordx4 v[176:177], off
	v_lshl_add_u64 v[176:177], v[228:229], 0, s[16:17]
	s_mov_b32 m0, s60
	s_nop 0
	global_load_lds_dwordx4 v[176:177], off
	v_lshl_add_u64 v[176:177], v[230:231], 0, s[16:17]
	s_mov_b32 m0, s61
	s_nop 0
	global_load_lds_dwordx4 v[176:177], off
	s_waitcnt vmcnt(8)
	s_waitcnt lgkmcnt(0)
	s_barrier
	s_setprio 1
	s_waitcnt lgkmcnt(0)
	v_mfma_f32_16x16x32_bf16 v[60:63], v[156:159], v[192:195], v[60:63]
	v_mfma_f32_16x16x32_bf16 v[56:59], v[164:167], v[192:195], v[56:59]
	v_mfma_f32_16x16x32_bf16 v[52:55], v[156:159], v[200:203], v[52:55]
	v_mfma_f32_16x16x32_bf16 v[48:51], v[164:167], v[200:203], v[48:51]
	v_mfma_f32_16x16x32_bf16 v[44:47], v[156:159], v[210:213], v[44:47]
	v_mfma_f32_16x16x32_bf16 v[40:43], v[164:167], v[210:213], v[40:43]
	v_mfma_f32_16x16x32_bf16 v[36:39], v[156:159], v[218:221], v[36:39]
	v_mfma_f32_16x16x32_bf16 v[32:35], v[164:167], v[218:221], v[32:35]
	v_mfma_f32_16x16x32_bf16 v[60:63], v[160:163], v[196:199], v[60:63]
	v_mfma_f32_16x16x32_bf16 v[56:59], v[168:171], v[196:199], v[56:59]
	v_mfma_f32_16x16x32_bf16 v[52:55], v[160:163], v[204:207], v[52:55]
	v_mfma_f32_16x16x32_bf16 v[48:51], v[168:171], v[204:207], v[48:51]
	v_mfma_f32_16x16x32_bf16 v[44:47], v[160:163], v[214:217], v[44:47]
	v_mfma_f32_16x16x32_bf16 v[40:43], v[168:171], v[214:217], v[40:43]
	v_mfma_f32_16x16x32_bf16 v[36:39], v[160:163], v[222:225], v[36:39]
	v_mfma_f32_16x16x32_bf16 v[32:35], v[168:171], v[222:225], v[32:35]
	v_mfma_f32_16x16x32_bf16 v[28:31], v[172:175], v[192:195], v[28:31]
	v_mfma_f32_16x16x32_bf16 v[24:27], v[184:187], v[192:195], v[24:27]
	v_mfma_f32_16x16x32_bf16 v[20:23], v[172:175], v[200:203], v[20:23]
	v_mfma_f32_16x16x32_bf16 v[16:19], v[184:187], v[200:203], v[16:19]
	v_mfma_f32_16x16x32_bf16 v[12:15], v[172:175], v[210:213], v[12:15]
	v_mfma_f32_16x16x32_bf16 v[8:11], v[184:187], v[210:213], v[8:11]
	v_mfma_f32_16x16x32_bf16 v[4:7], v[172:175], v[218:221], v[4:7]
	v_mfma_f32_16x16x32_bf16 v[0:3], v[184:187], v[218:221], v[0:3]
	v_mfma_f32_16x16x32_bf16 v[28:31], v[180:183], v[196:199], v[28:31]
	v_mfma_f32_16x16x32_bf16 v[24:27], v[188:191], v[196:199], v[24:27]
	v_mfma_f32_16x16x32_bf16 v[20:23], v[180:183], v[204:207], v[20:23]
	v_mfma_f32_16x16x32_bf16 v[16:19], v[188:191], v[204:207], v[16:19]
	v_mfma_f32_16x16x32_bf16 v[12:15], v[180:183], v[214:217], v[12:15]
	v_mfma_f32_16x16x32_bf16 v[8:11], v[188:191], v[214:217], v[8:11]
	v_mfma_f32_16x16x32_bf16 v[4:7], v[180:183], v[222:225], v[4:7]
	v_mfma_f32_16x16x32_bf16 v[0:3], v[188:191], v[222:225], v[0:3]
	s_setprio 0
	s_barrier
	s_movk_i32 s23, 0x100
	s_andn2_b64 vcc, exec, s[38:39]
	s_mov_b64 s[40:41], -1
	s_mov_b64 s[38:39], 0
	s_cbranch_vccz .LBB0_1327
	s_and_b64 vcc, exec, s[18:19]
	s_cbranch_vccz .LBB0_1330
	s_barrier

.LBB0_1461:
	ds_read_b128 v[144:147], v158
	ds_read_b128 v[162:165], v158 offset:1024
	ds_read_b128 v[166:169], v158 offset:2048
	ds_read_b128 v[170:173], v158 offset:3072
	ds_read_b128 v[174:177], v159
	ds_read_b128 v[180:183], v159 offset:1024
	ds_read_b128 v[184:187], v159 offset:2048
	ds_read_b128 v[188:191], v159 offset:3072
	s_add_u32 s22, s20, 0xffea0080
	s_addc_u32 s23, s21, -1
	s_cmpk_eq_i32 s47, 0x54
	s_cselect_b32 s25, s1, s23
	s_cselect_b32 s24, s0, s22
	s_cselect_b32 s23, s19, s46
	s_cselect_b32 s22, s18, s45
	v_lshl_add_u64 v[226:227], s[20:21], 0, v[138:139]
	s_add_i32 m0, s3, 0xc000
	ds_read_b128 v[192:195], v160
	ds_read_b128 v[196:199], v160 offset:1024
	ds_read_b128 v[200:203], v160 offset:2048
	ds_read_b128 v[204:207], v160 offset:3072
	ds_read_b128 v[210:213], v160 offset:4096
	ds_read_b128 v[214:217], v160 offset:5120
	ds_read_b128 v[218:221], v160 offset:6144
	ds_read_b128 v[222:225], v160 offset:7168
	global_load_lds_dwordx4 v[226:227], off
	v_lshl_add_u64 v[226:227], s[20:21], 0, v[140:141]
	s_add_i32 m0, s3, 0xe000
	s_nop 0
	global_load_lds_dwordx4 v[226:227], off
	s_waitcnt vmcnt(8)
	s_waitcnt lgkmcnt(0)
	s_barrier
	s_setprio 1
	s_waitcnt lgkmcnt(0)
	v_mfma_f32_16x16x32_bf16 v[124:127], v[144:147], v[192:195], v[124:127]
	v_mfma_f32_16x16x32_bf16 v[120:123], v[166:169], v[192:195], v[120:123]
	v_mfma_f32_16x16x32_bf16 v[108:111], v[144:147], v[200:203], v[108:111]
	v_mfma_f32_16x16x32_bf16 v[104:107], v[166:169], v[200:203], v[104:107]
	v_mfma_f32_16x16x32_bf16 v[92:95], v[144:147], v[210:213], v[92:95]
	v_mfma_f32_16x16x32_bf16 v[88:91], v[166:169], v[210:213], v[88:91]
	v_mfma_f32_16x16x32_bf16 v[76:79], v[144:147], v[218:221], v[76:79]
	v_mfma_f32_16x16x32_bf16 v[72:75], v[166:169], v[218:221], v[72:75]
	v_mfma_f32_16x16x32_bf16 v[124:127], v[162:165], v[196:199], v[124:127]
	v_mfma_f32_16x16x32_bf16 v[120:123], v[170:173], v[196:199], v[120:123]
	v_mfma_f32_16x16x32_bf16 v[108:111], v[162:165], v[204:207], v[108:111]
	v_mfma_f32_16x16x32_bf16 v[104:107], v[170:173], v[204:207], v[104:107]
	v_mfma_f32_16x16x32_bf16 v[92:95], v[162:165], v[214:217], v[92:95]
	v_mfma_f32_16x16x32_bf16 v[88:91], v[170:173], v[214:217], v[88:91]
	v_mfma_f32_16x16x32_bf16 v[76:79], v[162:165], v[222:225], v[76:79]
	v_mfma_f32_16x16x32_bf16 v[72:75], v[170:173], v[222:225], v[72:75]
	v_mfma_f32_16x16x32_bf16 v[116:119], v[174:177], v[192:195], v[116:119]
	v_mfma_f32_16x16x32_bf16 v[112:115], v[184:187], v[192:195], v[112:115]
	v_mfma_f32_16x16x32_bf16 v[100:103], v[174:177], v[200:203], v[100:103]
	v_mfma_f32_16x16x32_bf16 v[96:99], v[184:187], v[200:203], v[96:99]
	v_mfma_f32_16x16x32_bf16 v[84:87], v[174:177], v[210:213], v[84:87]
	v_mfma_f32_16x16x32_bf16 v[80:83], v[184:187], v[210:213], v[80:83]
	v_mfma_f32_16x16x32_bf16 v[68:71], v[174:177], v[218:221], v[68:71]
	v_mfma_f32_16x16x32_bf16 v[64:67], v[184:187], v[218:221], v[64:67]
	v_mfma_f32_16x16x32_bf16 v[116:119], v[180:183], v[196:199], v[116:119]
	v_mfma_f32_16x16x32_bf16 v[112:115], v[188:191], v[196:199], v[112:115]
	v_mfma_f32_16x16x32_bf16 v[100:103], v[180:183], v[204:207], v[100:103]
	v_mfma_f32_16x16x32_bf16 v[96:99], v[188:191], v[204:207], v[96:99]
	v_mfma_f32_16x16x32_bf16 v[84:87], v[180:183], v[214:217], v[84:87]
	v_mfma_f32_16x16x32_bf16 v[80:83], v[188:191], v[214:217], v[80:83]
	v_mfma_f32_16x16x32_bf16 v[68:71], v[180:183], v[222:225], v[68:71]
	v_mfma_f32_16x16x32_bf16 v[64:67], v[188:191], v[222:225], v[64:67]
	s_setprio 0
	s_barrier
	s_add_i32 s48, s39, s26
	v_lshl_add_u64 v[226:227], s[22:23], 0, v[132:133]
	s_mov_b32 m0, s48
	ds_read_b128 v[192:195], v160 offset:16384
	ds_read_b128 v[196:199], v160 offset:17408
	ds_read_b128 v[200:203], v160 offset:18432
	ds_read_b128 v[204:207], v160 offset:19456
	ds_read_b128 v[210:213], v160 offset:20480
	ds_read_b128 v[214:217], v160 offset:21504
	ds_read_b128 v[218:221], v160 offset:22528
	ds_read_b128 v[222:225], v160 offset:23552
	global_load_lds_dwordx4 v[226:227], off
	s_add_i32 m0, s48, 0x2000
	s_add_u32 s48, s22, 0x160000
	v_lshl_add_u64 v[228:229], s[22:23], 0, v[136:137]
	s_addc_u32 s49, s23, 0
	s_add_i32 s50, s40, s26
	global_load_lds_dwordx4 v[228:229], off
	v_lshl_add_u64 v[230:231], s[48:49], 0, v[132:133]
	s_mov_b32 m0, s50
	v_lshl_add_u64 v[232:233], s[24:25], 0, v[134:135]
	global_load_lds_dwordx4 v[230:231], off
	v_lshl_add_u64 v[230:231], s[48:49], 0, v[136:137]
	s_add_i32 m0, s50, 0x2000
	s_nop 0
	global_load_lds_dwordx4 v[230:231], off
	v_lshl_add_u64 v[230:231], s[24:25], 0, v[130:131]
	s_mov_b32 m0, s3
	s_nop 0
	global_load_lds_dwordx4 v[230:231], off
	s_mov_b32 m0, s28
	s_nop 0
	global_load_lds_dwordx4 v[232:233], off
	s_waitcnt vmcnt(8)
	s_waitcnt lgkmcnt(0)
	s_barrier
	s_setprio 1
	s_waitcnt lgkmcnt(0)
	v_mfma_f32_16x16x32_bf16 v[60:63], v[144:147], v[192:195], v[60:63]
	v_mfma_f32_16x16x32_bf16 v[56:59], v[166:169], v[192:195], v[56:59]
	v_mfma_f32_16x16x32_bf16 v[44:47], v[144:147], v[200:203], v[44:47]
	v_mfma_f32_16x16x32_bf16 v[40:43], v[166:169], v[200:203], v[40:43]
	v_mfma_f32_16x16x32_bf16 v[28:31], v[144:147], v[210:213], v[28:31]
	v_mfma_f32_16x16x32_bf16 v[24:27], v[166:169], v[210:213], v[24:27]
	v_mfma_f32_16x16x32_bf16 v[12:15], v[144:147], v[218:221], v[12:15]
	v_mfma_f32_16x16x32_bf16 v[8:11], v[166:169], v[218:221], v[8:11]
	v_mfma_f32_16x16x32_bf16 v[60:63], v[162:165], v[196:199], v[60:63]
	v_mfma_f32_16x16x32_bf16 v[56:59], v[170:173], v[196:199], v[56:59]
	v_mfma_f32_16x16x32_bf16 v[44:47], v[162:165], v[204:207], v[44:47]
	v_mfma_f32_16x16x32_bf16 v[40:43], v[170:173], v[204:207], v[40:43]
	v_mfma_f32_16x16x32_bf16 v[28:31], v[162:165], v[214:217], v[28:31]
	v_mfma_f32_16x16x32_bf16 v[24:27], v[170:173], v[214:217], v[24:27]
	v_mfma_f32_16x16x32_bf16 v[12:15], v[162:165], v[222:225], v[12:15]
	v_mfma_f32_16x16x32_bf16 v[8:11], v[170:173], v[222:225], v[8:11]
	v_mfma_f32_16x16x32_bf16 v[52:55], v[174:177], v[192:195], v[52:55]
	v_mfma_f32_16x16x32_bf16 v[48:51], v[184:187], v[192:195], v[48:51]
	v_mfma_f32_16x16x32_bf16 v[36:39], v[174:177], v[200:203], v[36:39]
	v_mfma_f32_16x16x32_bf16 v[32:35], v[184:187], v[200:203], v[32:35]
	v_mfma_f32_16x16x32_bf16 v[20:23], v[174:177], v[210:213], v[20:23]
	v_mfma_f32_16x16x32_bf16 v[16:19], v[184:187], v[210:213], v[16:19]
	v_mfma_f32_16x16x32_bf16 v[4:7], v[174:177], v[218:221], v[4:7]
	v_mfma_f32_16x16x32_bf16 v[0:3], v[184:187], v[218:221], v[0:3]
	v_mfma_f32_16x16x32_bf16 v[52:55], v[180:183], v[196:199], v[52:55]
	v_mfma_f32_16x16x32_bf16 v[48:51], v[188:191], v[196:199], v[48:51]
	v_mfma_f32_16x16x32_bf16 v[36:39], v[180:183], v[204:207], v[36:39]
	v_mfma_f32_16x16x32_bf16 v[32:35], v[188:191], v[204:207], v[32:35]
	v_mfma_f32_16x16x32_bf16 v[20:23], v[180:183], v[214:217], v[20:23]
	v_mfma_f32_16x16x32_bf16 v[16:19], v[188:191], v[214:217], v[16:19]
	v_mfma_f32_16x16x32_bf16 v[4:7], v[180:183], v[222:225], v[4:7]
	v_mfma_f32_16x16x32_bf16 v[0:3], v[188:191], v[222:225], v[0:3]
	s_setprio 0
	s_barrier
	s_add_i32 s48, 0, 0x18000
	v_add_u32_e32 v161, s48, v156
	s_add_i32 s49, 0, 0x1c000
	ds_read_b128 v[144:147], v161
	ds_read_b128 v[162:165], v161 offset:1024
	ds_read_b128 v[166:169], v161 offset:2048
	ds_read_b128 v[170:173], v161 offset:3072
	v_add_u32_e32 v161, s49, v156
	ds_read_b128 v[174:177], v161
	ds_read_b128 v[180:183], v161 offset:1024
	ds_read_b128 v[184:187], v161 offset:2048
	ds_read_b128 v[188:191], v161 offset:3072
	s_add_u32 s24, s24, 0x160000
	s_addc_u32 s25, s25, 0
	s_mov_b32 m0, s29
	v_lshl_add_u64 v[234:235], s[24:25], 0, v[130:131]
	ds_read_b128 v[192:195], v160 offset:32768
	ds_read_b128 v[196:199], v160 offset:33792
	ds_read_b128 v[200:203], v160 offset:34816
	ds_read_b128 v[204:207], v160 offset:35840
	ds_read_b128 v[210:213], v160 offset:36864
	ds_read_b128 v[214:217], v160 offset:37888
	ds_read_b128 v[218:221], v160 offset:38912
	ds_read_b128 v[222:225], v160 offset:39936
	global_load_lds_dwordx4 v[234:235], off
	v_lshl_add_u64 v[234:235], s[24:25], 0, v[134:135]
	s_mov_b32 m0, s36
	s_nop 0
	global_load_lds_dwordx4 v[234:235], off
	s_waitcnt vmcnt(8)
	s_waitcnt lgkmcnt(0)
	s_barrier
	s_setprio 1
	s_waitcnt lgkmcnt(0)
	v_mfma_f32_16x16x32_bf16 v[124:127], v[144:147], v[192:195], v[124:127]
	v_mfma_f32_16x16x32_bf16 v[120:123], v[166:169], v[192:195], v[120:123]
	v_mfma_f32_16x16x32_bf16 v[108:111], v[144:147], v[200:203], v[108:111]
	v_mfma_f32_16x16x32_bf16 v[104:107], v[166:169], v[200:203], v[104:107]
	v_mfma_f32_16x16x32_bf16 v[92:95], v[144:147], v[210:213], v[92:95]
	v_mfma_f32_16x16x32_bf16 v[88:91], v[166:169], v[210:213], v[88:91]
	v_mfma_f32_16x16x32_bf16 v[76:79], v[144:147], v[218:221], v[76:79]
	v_mfma_f32_16x16x32_bf16 v[72:75], v[166:169], v[218:221], v[72:75]
	v_mfma_f32_16x16x32_bf16 v[124:127], v[162:165], v[196:199], v[124:127]
	v_mfma_f32_16x16x32_bf16 v[120:123], v[170:173], v[196:199], v[120:123]
	v_mfma_f32_16x16x32_bf16 v[108:111], v[162:165], v[204:207], v[108:111]
	v_mfma_f32_16x16x32_bf16 v[104:107], v[170:173], v[204:207], v[104:107]
	v_mfma_f32_16x16x32_bf16 v[92:95], v[162:165], v[214:217], v[92:95]
	v_mfma_f32_16x16x32_bf16 v[88:91], v[170:173], v[214:217], v[88:91]
	v_mfma_f32_16x16x32_bf16 v[76:79], v[162:165], v[222:225], v[76:79]
	v_mfma_f32_16x16x32_bf16 v[72:75], v[170:173], v[222:225], v[72:75]
	v_mfma_f32_16x16x32_bf16 v[116:119], v[174:177], v[192:195], v[116:119]
	v_mfma_f32_16x16x32_bf16 v[112:115], v[184:187], v[192:195], v[112:115]
	v_mfma_f32_16x16x32_bf16 v[100:103], v[174:177], v[200:203], v[100:103]
	v_mfma_f32_16x16x32_bf16 v[96:99], v[184:187], v[200:203], v[96:99]
	v_mfma_f32_16x16x32_bf16 v[84:87], v[174:177], v[210:213], v[84:87]
	v_mfma_f32_16x16x32_bf16 v[80:83], v[184:187], v[210:213], v[80:83]
	v_mfma_f32_16x16x32_bf16 v[68:71], v[174:177], v[218:221], v[68:71]
	v_mfma_f32_16x16x32_bf16 v[64:67], v[184:187], v[218:221], v[64:67]
	v_mfma_f32_16x16x32_bf16 v[116:119], v[180:183], v[196:199], v[116:119]
	v_mfma_f32_16x16x32_bf16 v[112:115], v[188:191], v[196:199], v[112:115]
	v_mfma_f32_16x16x32_bf16 v[100:103], v[180:183], v[204:207], v[100:103]
	v_mfma_f32_16x16x32_bf16 v[96:99], v[188:191], v[204:207], v[96:99]
	v_mfma_f32_16x16x32_bf16 v[84:87], v[180:183], v[214:217], v[84:87]
	v_mfma_f32_16x16x32_bf16 v[80:83], v[188:191], v[214:217], v[80:83]
	v_mfma_f32_16x16x32_bf16 v[68:71], v[180:183], v[222:225], v[68:71]
	v_mfma_f32_16x16x32_bf16 v[64:67], v[188:191], v[222:225], v[64:67]
	s_setprio 0
	s_barrier
	s_add_i32 s24, s48, s26
	v_lshl_add_u64 v[226:227], v[226:227], 0, s[14:15]
	s_mov_b32 m0, s24
	ds_read_b128 v[192:195], v160 offset:49152
	ds_read_b128 v[196:199], v160 offset:50176
	ds_read_b128 v[200:203], v160 offset:51200
	ds_read_b128 v[204:207], v160 offset:52224
	ds_read_b128 v[210:213], v160 offset:53248
	ds_read_b128 v[214:217], v160 offset:54272
	ds_read_b128 v[218:221], v160 offset:55296
	ds_read_b128 v[222:225], v160 offset:56320
	global_load_lds_dwordx4 v[226:227], off
	s_add_i32 m0, s24, 0x2000
	s_add_u32 s22, s22, 0x160080
	v_lshl_add_u64 v[226:227], v[228:229], 0, s[14:15]
	s_addc_u32 s23, s23, 0
	s_add_i32 s24, s49, s26
	global_load_lds_dwordx4 v[226:227], off
	v_lshl_add_u64 v[226:227], s[22:23], 0, v[132:133]
	s_mov_b32 m0, s24
	s_nop 0
	global_load_lds_dwordx4 v[226:227], off
	v_lshl_add_u64 v[226:227], s[22:23], 0, v[136:137]
	s_add_i32 m0, s24, 0x2000
	s_nop 0
	global_load_lds_dwordx4 v[226:227], off
	v_lshl_add_u64 v[226:227], v[230:231], 0, s[14:15]
	s_mov_b32 m0, s2
	s_nop 0
	global_load_lds_dwordx4 v[226:227], off
	v_lshl_add_u64 v[226:227], v[232:233], 0, s[14:15]
	s_mov_b32 m0, s37
	s_nop 0
	global_load_lds_dwordx4 v[226:227], off
	s_waitcnt vmcnt(8)
	s_waitcnt lgkmcnt(0)
	s_barrier
	s_setprio 1
	s_waitcnt lgkmcnt(0)
	v_mfma_f32_16x16x32_bf16 v[60:63], v[144:147], v[192:195], v[60:63]
	v_mfma_f32_16x16x32_bf16 v[56:59], v[166:169], v[192:195], v[56:59]
	v_mfma_f32_16x16x32_bf16 v[44:47], v[144:147], v[200:203], v[44:47]
	v_mfma_f32_16x16x32_bf16 v[40:43], v[166:169], v[200:203], v[40:43]
	v_mfma_f32_16x16x32_bf16 v[28:31], v[144:147], v[210:213], v[28:31]
	v_mfma_f32_16x16x32_bf16 v[24:27], v[166:169], v[210:213], v[24:27]
	v_mfma_f32_16x16x32_bf16 v[12:15], v[144:147], v[218:221], v[12:15]
	v_mfma_f32_16x16x32_bf16 v[8:11], v[166:169], v[218:221], v[8:11]
	v_mfma_f32_16x16x32_bf16 v[60:63], v[162:165], v[196:199], v[60:63]
	v_mfma_f32_16x16x32_bf16 v[56:59], v[170:173], v[196:199], v[56:59]
	v_mfma_f32_16x16x32_bf16 v[44:47], v[162:165], v[204:207], v[44:47]
	v_mfma_f32_16x16x32_bf16 v[40:43], v[170:173], v[204:207], v[40:43]
	v_mfma_f32_16x16x32_bf16 v[28:31], v[162:165], v[214:217], v[28:31]
	v_mfma_f32_16x16x32_bf16 v[24:27], v[170:173], v[214:217], v[24:27]
	v_mfma_f32_16x16x32_bf16 v[12:15], v[162:165], v[222:225], v[12:15]
	v_mfma_f32_16x16x32_bf16 v[8:11], v[170:173], v[222:225], v[8:11]
	v_mfma_f32_16x16x32_bf16 v[52:55], v[174:177], v[192:195], v[52:55]
	v_mfma_f32_16x16x32_bf16 v[48:51], v[184:187], v[192:195], v[48:51]
	v_mfma_f32_16x16x32_bf16 v[36:39], v[174:177], v[200:203], v[36:39]
	v_mfma_f32_16x16x32_bf16 v[32:35], v[184:187], v[200:203], v[32:35]
	v_mfma_f32_16x16x32_bf16 v[20:23], v[174:177], v[210:213], v[20:23]
	v_mfma_f32_16x16x32_bf16 v[16:19], v[184:187], v[210:213], v[16:19]
	v_mfma_f32_16x16x32_bf16 v[4:7], v[174:177], v[218:221], v[4:7]
	v_mfma_f32_16x16x32_bf16 v[0:3], v[184:187], v[218:221], v[0:3]
	v_mfma_f32_16x16x32_bf16 v[52:55], v[180:183], v[196:199], v[52:55]
	v_mfma_f32_16x16x32_bf16 v[48:51], v[188:191], v[196:199], v[48:51]
	v_mfma_f32_16x16x32_bf16 v[36:39], v[180:183], v[204:207], v[36:39]
	v_mfma_f32_16x16x32_bf16 v[32:35], v[188:191], v[204:207], v[32:35]
	v_mfma_f32_16x16x32_bf16 v[20:23], v[180:183], v[214:217], v[20:23]
	v_mfma_f32_16x16x32_bf16 v[16:19], v[188:191], v[214:217], v[16:19]
	v_mfma_f32_16x16x32_bf16 v[4:7], v[180:183], v[222:225], v[4:7]
	v_mfma_f32_16x16x32_bf16 v[0:3], v[188:191], v[222:225], v[0:3]
	s_setprio 0
	s_barrier
	s_add_i32 s47, s47, 2
	s_add_u32 s20, s20, 0x100
	s_addc_u32 s21, s21, 0
	s_add_u32 s45, s45, 0x100
	s_addc_u32 s46, s46, 0
	s_cmpk_gt_u32 s47, 0x55
	s_cbranch_scc0 .LBB0_1461
	s_and_b64 vcc, exec, s[16:17]
	s_cbranch_vccz .LBB0_1464
	s_barrier

.LBB0_1482:
	ds_read_b128 v[152:155], v129
	ds_read_b128 v[156:159], v129 offset:1024
	ds_read_b128 v[160:163], v129 offset:2048
	ds_read_b128 v[164:167], v129 offset:3072
	ds_read_b128 v[168:171], v145
	ds_read_b128 v[172:175], v145 offset:1024
	ds_read_b128 v[180:183], v145 offset:2048
	ds_read_b128 v[184:187], v145 offset:3072
	s_add_u32 s26, s24, 0xffea0080
	s_addc_u32 s27, s25, -1
	s_cmp_eq_u32 s71, 18
	s_cselect_b32 s29, s19, s27
	s_cselect_b32 s28, s18, s26
	s_cselect_b32 s27, s21, s70
	s_cselect_b32 s26, s20, s23
	v_lshl_add_u64 v[176:177], s[24:25], 0, v[140:141]
	s_add_i32 m0, s11, 0xc000
	ds_read_b128 v[188:191], v146
	ds_read_b128 v[192:195], v146 offset:1024
	ds_read_b128 v[196:199], v146 offset:2048
	ds_read_b128 v[200:203], v146 offset:3072
	ds_read_b128 v[204:207], v146 offset:4096
	ds_read_b128 v[208:211], v146 offset:5120
	ds_read_b128 v[212:215], v146 offset:6144
	ds_read_b128 v[216:219], v146 offset:7168
	global_load_lds_dwordx4 v[176:177], off
	v_lshl_add_u64 v[176:177], s[24:25], 0, v[142:143]
	s_add_i32 m0, s11, 0xe000
	s_nop 0
	global_load_lds_dwordx4 v[176:177], off
	s_waitcnt vmcnt(8)
	s_waitcnt lgkmcnt(0)
	s_barrier
	s_setprio 1
	s_waitcnt lgkmcnt(0)
	v_mfma_f32_16x16x32_bf16 v[124:127], v[152:155], v[188:191], v[124:127]
	v_mfma_f32_16x16x32_bf16 v[120:123], v[160:163], v[188:191], v[120:123]
	v_mfma_f32_16x16x32_bf16 v[116:119], v[152:155], v[196:199], v[116:119]
	v_mfma_f32_16x16x32_bf16 v[112:115], v[160:163], v[196:199], v[112:115]
	v_mfma_f32_16x16x32_bf16 v[108:111], v[152:155], v[204:207], v[108:111]
	v_mfma_f32_16x16x32_bf16 v[104:107], v[160:163], v[204:207], v[104:107]
	v_mfma_f32_16x16x32_bf16 v[100:103], v[152:155], v[212:215], v[100:103]
	v_mfma_f32_16x16x32_bf16 v[96:99], v[160:163], v[212:215], v[96:99]
	v_mfma_f32_16x16x32_bf16 v[124:127], v[156:159], v[192:195], v[124:127]
	v_mfma_f32_16x16x32_bf16 v[120:123], v[164:167], v[192:195], v[120:123]
	v_mfma_f32_16x16x32_bf16 v[116:119], v[156:159], v[200:203], v[116:119]
	v_mfma_f32_16x16x32_bf16 v[112:115], v[164:167], v[200:203], v[112:115]
	v_mfma_f32_16x16x32_bf16 v[108:111], v[156:159], v[208:211], v[108:111]
	v_mfma_f32_16x16x32_bf16 v[104:107], v[164:167], v[208:211], v[104:107]
	v_mfma_f32_16x16x32_bf16 v[100:103], v[156:159], v[216:219], v[100:103]
	v_mfma_f32_16x16x32_bf16 v[96:99], v[164:167], v[216:219], v[96:99]
	v_mfma_f32_16x16x32_bf16 v[92:95], v[168:171], v[188:191], v[92:95]
	v_mfma_f32_16x16x32_bf16 v[88:91], v[180:183], v[188:191], v[88:91]
	v_mfma_f32_16x16x32_bf16 v[84:87], v[168:171], v[196:199], v[84:87]
	v_mfma_f32_16x16x32_bf16 v[80:83], v[180:183], v[196:199], v[80:83]
	v_mfma_f32_16x16x32_bf16 v[76:79], v[168:171], v[204:207], v[76:79]
	v_mfma_f32_16x16x32_bf16 v[72:75], v[180:183], v[204:207], v[72:75]
	v_mfma_f32_16x16x32_bf16 v[68:71], v[168:171], v[212:215], v[68:71]
	v_mfma_f32_16x16x32_bf16 v[64:67], v[180:183], v[212:215], v[64:67]
	v_mfma_f32_16x16x32_bf16 v[92:95], v[172:175], v[192:195], v[92:95]
	v_mfma_f32_16x16x32_bf16 v[88:91], v[184:187], v[192:195], v[88:91]
	v_mfma_f32_16x16x32_bf16 v[84:87], v[172:175], v[200:203], v[84:87]
	v_mfma_f32_16x16x32_bf16 v[80:83], v[184:187], v[200:203], v[80:83]
	v_mfma_f32_16x16x32_bf16 v[76:79], v[172:175], v[208:211], v[76:79]
	v_mfma_f32_16x16x32_bf16 v[72:75], v[184:187], v[208:211], v[72:75]
	v_mfma_f32_16x16x32_bf16 v[68:71], v[172:175], v[216:219], v[68:71]
	v_mfma_f32_16x16x32_bf16 v[64:67], v[184:187], v[216:219], v[64:67]
	s_setprio 0
	s_barrier
	s_add_i32 s72, s50, s3
	v_lshl_add_u64 v[176:177], s[26:27], 0, v[132:133]
	s_mov_b32 m0, s72
	ds_read_b128 v[188:191], v146 offset:16384
	ds_read_b128 v[192:195], v146 offset:17408
	ds_read_b128 v[196:199], v146 offset:18432
	ds_read_b128 v[200:203], v146 offset:19456
	ds_read_b128 v[204:207], v146 offset:20480
	ds_read_b128 v[208:211], v146 offset:21504
	ds_read_b128 v[212:215], v146 offset:22528
	ds_read_b128 v[216:219], v146 offset:23552
	global_load_lds_dwordx4 v[176:177], off
	s_add_i32 m0, s72, 0x2000
	s_add_u32 s72, s26, 0x160000
	v_lshl_add_u64 v[220:221], s[26:27], 0, v[136:137]
	s_addc_u32 s73, s27, 0
	s_add_i32 s74, s51, s3
	global_load_lds_dwordx4 v[220:221], off
	v_lshl_add_u64 v[222:223], s[72:73], 0, v[132:133]
	s_mov_b32 m0, s74
	v_lshl_add_u64 v[224:225], s[28:29], 0, v[134:135]
	global_load_lds_dwordx4 v[222:223], off
	v_lshl_add_u64 v[222:223], s[72:73], 0, v[136:137]
	s_add_i32 m0, s74, 0x2000
	s_nop 0
	global_load_lds_dwordx4 v[222:223], off
	v_lshl_add_u64 v[222:223], s[28:29], 0, v[130:131]
	s_mov_b32 m0, s11
	s_nop 0
	global_load_lds_dwordx4 v[222:223], off
	s_mov_b32 m0, s36
	s_nop 0
	global_load_lds_dwordx4 v[224:225], off
	s_waitcnt vmcnt(8)
	s_waitcnt lgkmcnt(0)
	s_barrier
	s_setprio 1
	s_waitcnt lgkmcnt(0)
	v_mfma_f32_16x16x32_bf16 v[60:63], v[152:155], v[188:191], v[60:63]
	v_mfma_f32_16x16x32_bf16 v[56:59], v[160:163], v[188:191], v[56:59]
	v_mfma_f32_16x16x32_bf16 v[52:55], v[152:155], v[196:199], v[52:55]
	v_mfma_f32_16x16x32_bf16 v[48:51], v[160:163], v[196:199], v[48:51]
	v_mfma_f32_16x16x32_bf16 v[44:47], v[152:155], v[204:207], v[44:47]
	v_mfma_f32_16x16x32_bf16 v[40:43], v[160:163], v[204:207], v[40:43]
	v_mfma_f32_16x16x32_bf16 v[36:39], v[152:155], v[212:215], v[36:39]
	v_mfma_f32_16x16x32_bf16 v[32:35], v[160:163], v[212:215], v[32:35]
	v_mfma_f32_16x16x32_bf16 v[60:63], v[156:159], v[192:195], v[60:63]
	v_mfma_f32_16x16x32_bf16 v[56:59], v[164:167], v[192:195], v[56:59]
	v_mfma_f32_16x16x32_bf16 v[52:55], v[156:159], v[200:203], v[52:55]
	v_mfma_f32_16x16x32_bf16 v[48:51], v[164:167], v[200:203], v[48:51]
	v_mfma_f32_16x16x32_bf16 v[44:47], v[156:159], v[208:211], v[44:47]
	v_mfma_f32_16x16x32_bf16 v[40:43], v[164:167], v[208:211], v[40:43]
	v_mfma_f32_16x16x32_bf16 v[36:39], v[156:159], v[216:219], v[36:39]
	v_mfma_f32_16x16x32_bf16 v[32:35], v[164:167], v[216:219], v[32:35]
	v_mfma_f32_16x16x32_bf16 v[28:31], v[168:171], v[188:191], v[28:31]
	v_mfma_f32_16x16x32_bf16 v[24:27], v[180:183], v[188:191], v[24:27]
	v_mfma_f32_16x16x32_bf16 v[20:23], v[168:171], v[196:199], v[20:23]
	v_mfma_f32_16x16x32_bf16 v[16:19], v[180:183], v[196:199], v[16:19]
	v_mfma_f32_16x16x32_bf16 v[12:15], v[168:171], v[204:207], v[12:15]
	v_mfma_f32_16x16x32_bf16 v[8:11], v[180:183], v[204:207], v[8:11]
	v_mfma_f32_16x16x32_bf16 v[4:7], v[168:171], v[212:215], v[4:7]
	v_mfma_f32_16x16x32_bf16 v[0:3], v[180:183], v[212:215], v[0:3]
	v_mfma_f32_16x16x32_bf16 v[28:31], v[172:175], v[192:195], v[28:31]
	v_mfma_f32_16x16x32_bf16 v[24:27], v[184:187], v[192:195], v[24:27]
	v_mfma_f32_16x16x32_bf16 v[20:23], v[172:175], v[200:203], v[20:23]
	v_mfma_f32_16x16x32_bf16 v[16:19], v[184:187], v[200:203], v[16:19]
	v_mfma_f32_16x16x32_bf16 v[12:15], v[172:175], v[208:211], v[12:15]
	v_mfma_f32_16x16x32_bf16 v[8:11], v[184:187], v[208:211], v[8:11]
	v_mfma_f32_16x16x32_bf16 v[4:7], v[172:175], v[216:219], v[4:7]
	v_mfma_f32_16x16x32_bf16 v[0:3], v[184:187], v[216:219], v[0:3]
	s_setprio 0
	s_barrier
	s_add_i32 s72, 0, 0x18000
	v_add_u32_e32 v147, s72, v144
	s_add_i32 s73, 0, 0x1c000
	ds_read_b128 v[152:155], v147
	ds_read_b128 v[156:159], v147 offset:1024
	ds_read_b128 v[160:163], v147 offset:2048
	ds_read_b128 v[164:167], v147 offset:3072
	v_add_u32_e32 v147, s73, v144
	ds_read_b128 v[168:171], v147
	ds_read_b128 v[172:175], v147 offset:1024
	ds_read_b128 v[180:183], v147 offset:2048
	ds_read_b128 v[184:187], v147 offset:3072
	s_add_u32 s28, s28, 0x160000
	s_addc_u32 s29, s29, 0
	s_mov_b32 m0, s37
	v_lshl_add_u64 v[226:227], s[28:29], 0, v[130:131]
	ds_read_b128 v[188:191], v146 offset:32768
	ds_read_b128 v[192:195], v146 offset:33792
	ds_read_b128 v[196:199], v146 offset:34816
	ds_read_b128 v[200:203], v146 offset:35840
	ds_read_b128 v[204:207], v146 offset:36864
	ds_read_b128 v[208:211], v146 offset:37888
	ds_read_b128 v[212:215], v146 offset:38912
	ds_read_b128 v[216:219], v146 offset:39936
	global_load_lds_dwordx4 v[226:227], off
	v_lshl_add_u64 v[226:227], s[28:29], 0, v[134:135]
	s_mov_b32 m0, s38
	s_nop 0
	global_load_lds_dwordx4 v[226:227], off
	s_waitcnt vmcnt(8)
	s_waitcnt lgkmcnt(0)
	s_barrier
	s_setprio 1
	s_waitcnt lgkmcnt(0)
	v_mfma_f32_16x16x32_bf16 v[124:127], v[152:155], v[188:191], v[124:127]
	v_mfma_f32_16x16x32_bf16 v[120:123], v[160:163], v[188:191], v[120:123]
	v_mfma_f32_16x16x32_bf16 v[116:119], v[152:155], v[196:199], v[116:119]
	v_mfma_f32_16x16x32_bf16 v[112:115], v[160:163], v[196:199], v[112:115]
	v_mfma_f32_16x16x32_bf16 v[108:111], v[152:155], v[204:207], v[108:111]
	v_mfma_f32_16x16x32_bf16 v[104:107], v[160:163], v[204:207], v[104:107]
	v_mfma_f32_16x16x32_bf16 v[100:103], v[152:155], v[212:215], v[100:103]
	v_mfma_f32_16x16x32_bf16 v[96:99], v[160:163], v[212:215], v[96:99]
	v_mfma_f32_16x16x32_bf16 v[124:127], v[156:159], v[192:195], v[124:127]
	v_mfma_f32_16x16x32_bf16 v[120:123], v[164:167], v[192:195], v[120:123]
	v_mfma_f32_16x16x32_bf16 v[116:119], v[156:159], v[200:203], v[116:119]
	v_mfma_f32_16x16x32_bf16 v[112:115], v[164:167], v[200:203], v[112:115]
	v_mfma_f32_16x16x32_bf16 v[108:111], v[156:159], v[208:211], v[108:111]
	v_mfma_f32_16x16x32_bf16 v[104:107], v[164:167], v[208:211], v[104:107]
	v_mfma_f32_16x16x32_bf16 v[100:103], v[156:159], v[216:219], v[100:103]
	v_mfma_f32_16x16x32_bf16 v[96:99], v[164:167], v[216:219], v[96:99]
	v_mfma_f32_16x16x32_bf16 v[92:95], v[168:171], v[188:191], v[92:95]
	v_mfma_f32_16x16x32_bf16 v[88:91], v[180:183], v[188:191], v[88:91]
	v_mfma_f32_16x16x32_bf16 v[84:87], v[168:171], v[196:199], v[84:87]
	v_mfma_f32_16x16x32_bf16 v[80:83], v[180:183], v[196:199], v[80:83]
	v_mfma_f32_16x16x32_bf16 v[76:79], v[168:171], v[204:207], v[76:79]
	v_mfma_f32_16x16x32_bf16 v[72:75], v[180:183], v[204:207], v[72:75]
	v_mfma_f32_16x16x32_bf16 v[68:71], v[168:171], v[212:215], v[68:71]
	v_mfma_f32_16x16x32_bf16 v[64:67], v[180:183], v[212:215], v[64:67]
	v_mfma_f32_16x16x32_bf16 v[92:95], v[172:175], v[192:195], v[92:95]
	v_mfma_f32_16x16x32_bf16 v[88:91], v[184:187], v[192:195], v[88:91]
	v_mfma_f32_16x16x32_bf16 v[84:87], v[172:175], v[200:203], v[84:87]
	v_mfma_f32_16x16x32_bf16 v[80:83], v[184:187], v[200:203], v[80:83]
	v_mfma_f32_16x16x32_bf16 v[76:79], v[172:175], v[208:211], v[76:79]
	v_mfma_f32_16x16x32_bf16 v[72:75], v[184:187], v[208:211], v[72:75]
	v_mfma_f32_16x16x32_bf16 v[68:71], v[172:175], v[216:219], v[68:71]
	v_mfma_f32_16x16x32_bf16 v[64:67], v[184:187], v[216:219], v[64:67]
	s_setprio 0
	s_barrier
	s_add_i32 s28, s72, s3
	v_lshl_add_u64 v[176:177], v[176:177], 0, s[14:15]
	s_mov_b32 m0, s28
	ds_read_b128 v[188:191], v146 offset:49152
	ds_read_b128 v[192:195], v146 offset:50176
	ds_read_b128 v[196:199], v146 offset:51200
	ds_read_b128 v[200:203], v146 offset:52224
	ds_read_b128 v[204:207], v146 offset:53248
	ds_read_b128 v[208:211], v146 offset:54272
	ds_read_b128 v[212:215], v146 offset:55296
	ds_read_b128 v[216:219], v146 offset:56320
	global_load_lds_dwordx4 v[176:177], off
	s_add_i32 m0, s28, 0x2000
	s_add_u32 s26, s26, 0x160080
	v_lshl_add_u64 v[176:177], v[220:221], 0, s[14:15]
	s_addc_u32 s27, s27, 0
	s_add_i32 s28, s73, s3
	global_load_lds_dwordx4 v[176:177], off
	v_lshl_add_u64 v[176:177], s[26:27], 0, v[132:133]
	s_mov_b32 m0, s28
	s_nop 0
	global_load_lds_dwordx4 v[176:177], off
	v_lshl_add_u64 v[176:177], s[26:27], 0, v[136:137]
	s_add_i32 m0, s28, 0x2000
	s_nop 0
	global_load_lds_dwordx4 v[176:177], off
	v_lshl_add_u64 v[176:177], v[222:223], 0, s[14:15]
	s_mov_b32 m0, s44
	s_nop 0
	global_load_lds_dwordx4 v[176:177], off
	v_lshl_add_u64 v[176:177], v[224:225], 0, s[14:15]
	s_mov_b32 m0, s45
	s_nop 0
	global_load_lds_dwordx4 v[176:177], off
	s_waitcnt vmcnt(8)
	s_waitcnt lgkmcnt(0)
	s_barrier
	s_setprio 1
	s_waitcnt lgkmcnt(0)
	v_mfma_f32_16x16x32_bf16 v[60:63], v[152:155], v[188:191], v[60:63]
	v_mfma_f32_16x16x32_bf16 v[56:59], v[160:163], v[188:191], v[56:59]
	v_mfma_f32_16x16x32_bf16 v[52:55], v[152:155], v[196:199], v[52:55]
	v_mfma_f32_16x16x32_bf16 v[48:51], v[160:163], v[196:199], v[48:51]
	v_mfma_f32_16x16x32_bf16 v[44:47], v[152:155], v[204:207], v[44:47]
	v_mfma_f32_16x16x32_bf16 v[40:43], v[160:163], v[204:207], v[40:43]
	v_mfma_f32_16x16x32_bf16 v[36:39], v[152:155], v[212:215], v[36:39]
	v_mfma_f32_16x16x32_bf16 v[32:35], v[160:163], v[212:215], v[32:35]
	v_mfma_f32_16x16x32_bf16 v[60:63], v[156:159], v[192:195], v[60:63]
	v_mfma_f32_16x16x32_bf16 v[56:59], v[164:167], v[192:195], v[56:59]
	v_mfma_f32_16x16x32_bf16 v[52:55], v[156:159], v[200:203], v[52:55]
	v_mfma_f32_16x16x32_bf16 v[48:51], v[164:167], v[200:203], v[48:51]
	v_mfma_f32_16x16x32_bf16 v[44:47], v[156:159], v[208:211], v[44:47]
	v_mfma_f32_16x16x32_bf16 v[40:43], v[164:167], v[208:211], v[40:43]
	v_mfma_f32_16x16x32_bf16 v[36:39], v[156:159], v[216:219], v[36:39]
	v_mfma_f32_16x16x32_bf16 v[32:35], v[164:167], v[216:219], v[32:35]
	v_mfma_f32_16x16x32_bf16 v[28:31], v[168:171], v[188:191], v[28:31]
	v_mfma_f32_16x16x32_bf16 v[24:27], v[180:183], v[188:191], v[24:27]
	v_mfma_f32_16x16x32_bf16 v[20:23], v[168:171], v[196:199], v[20:23]
	v_mfma_f32_16x16x32_bf16 v[16:19], v[180:183], v[196:199], v[16:19]
	v_mfma_f32_16x16x32_bf16 v[12:15], v[168:171], v[204:207], v[12:15]
	v_mfma_f32_16x16x32_bf16 v[8:11], v[180:183], v[204:207], v[8:11]
	v_mfma_f32_16x16x32_bf16 v[4:7], v[168:171], v[212:215], v[4:7]
	v_mfma_f32_16x16x32_bf16 v[0:3], v[180:183], v[212:215], v[0:3]
	v_mfma_f32_16x16x32_bf16 v[28:31], v[172:175], v[192:195], v[28:31]
	v_mfma_f32_16x16x32_bf16 v[24:27], v[184:187], v[192:195], v[24:27]
	v_mfma_f32_16x16x32_bf16 v[20:23], v[172:175], v[200:203], v[20:23]
	v_mfma_f32_16x16x32_bf16 v[16:19], v[184:187], v[200:203], v[16:19]
	v_mfma_f32_16x16x32_bf16 v[12:15], v[172:175], v[208:211], v[12:15]
	v_mfma_f32_16x16x32_bf16 v[8:11], v[184:187], v[208:211], v[8:11]
	v_mfma_f32_16x16x32_bf16 v[4:7], v[172:175], v[216:219], v[4:7]
	v_mfma_f32_16x16x32_bf16 v[0:3], v[184:187], v[216:219], v[0:3]
	s_setprio 0
	s_barrier
	s_add_i32 s71, s71, 2
	s_add_u32 s24, s24, 0x100
	s_addc_u32 s25, s25, 0
	s_add_u32 s23, s23, 0x100
	s_addc_u32 s70, s70, 0
	s_cmp_gt_u32 s71, 19
	s_cbranch_scc0 .LBB0_1482
	s_and_b64 vcc, exec, s[16:17]
	s_cbranch_vccz .LBB0_1485
	s_barrier
